# FFN-gate epilogue: conv taps and bias staged once per tile into a per-wave LDS table by one LDS-DMA; 32 dependent global loads became ds_read_b128
# speedup vs baseline: 1.0049x; 1.0049x over previous
; #define PG8_STAGE(bufoff, gbase, voff) do { _Pragma("unroll") for (int _i = 0; _i < 2; ++_i) \
;         __builtin_amdgcn_global_load_lds((const unsigned*)((const char*)(gbase) + (voff)[_i]), (LAS unsigned*)(lds + (bufoff) + ldsw + _i * 8192), 16, 0, 0); } while (0)
; #define PG8_LDA(dst, b, h) do { _Pragma("unroll") for (int m = 0; m < 4; ++m) _Pragma("unroll") for (int k = 0; k < 2; ++k) dst[m][k] = *(const LAS bf16x8*)(lds + PG8_SA(b, h) + aoff + m * 2048 + k * 1024); } while (0)
; #define PG8_LDB(dst, b, h) do { _Pragma("unroll") for (int n = 0; n < 2; ++n) _Pragma("unroll") for (int k = 0; k < 2; ++k) dst[n][k] = *(const LAS bf16x8*)(lds + PG8_SB(b, h) + boff + n * 2048 + k * 1024); } while (0)
; #define PG8_MMA(ai, bj, At, Bt) do { __builtin_amdgcn_s_setprio(1); _Pragma("unroll") for (int m = 0; m < 4; ++m) _Pragma("unroll") for (int n = 0; n < 2; ++n) _Pragma("unroll") for (int k = 0; k < 2; ++k) \
;         acc[ai][bj][m][n] = __builtin_amdgcn_mfma_f32_16x16x32_bf16(Bt[n][k], At[m][k], acc[ai][bj][m][n], 0, 0, 0); __builtin_amdgcn_s_setprio(0); } while (0)
; #define PG8_WAIT_V(n) asm volatile("s_waitcnt vmcnt(" #n ")" ::: "memory")
; #define PG8_WAIT_L(n) asm volatile("s_waitcnt lgkmcnt(" #n ")" ::: "memory")
; #define PG8_BAR __builtin_amdgcn_s_barrier()
; #define PG8_SCHED __builtin_amdgcn_sched_barrier(0)
; template <class Epi>
; __device__ __forceinline__ void gemm_phase(ldsp lds, const Gemm g, const StaticOrder& S, const Epi& E, const int tid) {
;     ...
;         for (int t = 0; t < nt; t += 2) {
;             const bool last = (t == nt - 2);
;             const char* a1 = cA + (size_t)(t + 1) * kstep;
;             const char* a2 = last ? nA : cA + (size_t)(t + 2) * kstep; const char* b2 = last ? nB : cB + (size_t)(t + 2) * kstep;
;             const char* a3 = a2 + kstep; const char* b3 = b2 + kstep;
;             PG8_LDB(B0, 0, 0); PG8_LDB(B1, 0, 1); PG8_SCHED; PG8_LDA(At, 0, 0); PG8_STAGE(PG8_SA(1, 1), a1 + hstepA, voffA);
;             PG8_WAIT_V(8); PG8_WAIT_L(0); PG8_BAR; PG8_MMA(0, 0, At, B0); PG8_MMA(0, 1, At, B1); PG8_BAR; PG8_SCHED;
;             PG8_LDA(At, 0, 1); PG8_STAGE(PG8_SB(0, 0), b2, voffB); PG8_STAGE(PG8_SB(0, 1), b2 + hstepB, voffB); PG8_STAGE(PG8_SA(0, 0), a2, voffA);
;             PG8_WAIT_V(8); PG8_WAIT_L(0); PG8_BAR; PG8_MMA(1, 0, At, B0); PG8_MMA(1, 1, At, B1); PG8_BAR; PG8_SCHED;
.LBB0_1043:
	s_add_u32 s10, s6, 0xfffc0080
	s_addc_u32 s11, s7, -1
	s_add_i32 s29, 0, 0x10000
	s_cmp_eq_u32 s27, 12
	s_cselect_b32 s13, s0, s11
	s_cselect_b32 s12, s1, s10
	v_add_u32_e32 v96, s29, v184
	s_cselect_b32 s11, s3, s23
	s_cselect_b32 s10, s9, s22
	s_add_i32 s38, 0, 0x14000
	ds_read_b128 v[130:133], v96
	ds_read_b128 v[134:137], v96 offset:1024
	ds_read_b128 v[138:141], v96 offset:2048
	ds_read_b128 v[142:145], v96 offset:3072
	v_add_u32_e32 v96, s38, v184
	ds_read_b128 v[158:161], v96
	ds_read_b128 v[162:165], v96 offset:1024
	ds_read_b128 v[166:169], v96 offset:2048
	ds_read_b128 v[170:173], v96 offset:3072
	v_lshl_add_u64 v[194:195], s[6:7], 0, v[154:155]
	s_add_i32 m0, s85, 0xc000
	ds_read_b128 v[174:177], v185
	ds_read_b128 v[178:181], v185 offset:1024
	ds_read_b128 v[186:189], v185 offset:2048
	ds_read_b128 v[190:193], v185 offset:3072
	ds_read_b128 v[226:229], v185 offset:4096
	ds_read_b128 v[230:233], v185 offset:5120
	ds_read_b128 v[234:237], v185 offset:6144
	ds_read_b128 v[238:241], v185 offset:7168
	global_load_lds_dwordx4 v[194:195], off
	v_lshl_add_u64 v[194:195], s[6:7], 0, v[156:157]
	s_add_i32 m0, s85, 0xe000
	s_nop 0
	global_load_lds_dwordx4 v[194:195], off
	s_waitcnt vmcnt(8)
	s_waitcnt lgkmcnt(0)
	s_barrier
	s_setprio 1
	s_waitcnt lgkmcnt(0)
	v_mfma_f32_16x16x32_bf16 v[110:113], v[130:133], v[174:177], v[110:113]
	v_mfma_f32_16x16x32_bf16 v[76:79], v[138:141], v[174:177], v[76:79]
	v_mfma_f32_16x16x32_bf16 v[126:129], v[130:133], v[186:189], v[126:129]
	v_mfma_f32_16x16x32_bf16 v[92:95], v[138:141], v[186:189], v[92:95]
	v_mfma_f32_16x16x32_bf16 v[122:125], v[130:133], v[226:229], v[122:125]
	v_mfma_f32_16x16x32_bf16 v[88:91], v[138:141], v[226:229], v[88:91]
	v_mfma_f32_16x16x32_bf16 v[106:109], v[130:133], v[234:237], v[106:109]
	v_mfma_f32_16x16x32_bf16 v[72:75], v[138:141], v[234:237], v[72:75]
	v_mfma_f32_16x16x32_bf16 v[110:113], v[134:137], v[178:181], v[110:113]
	v_mfma_f32_16x16x32_bf16 v[76:79], v[142:145], v[178:181], v[76:79]
	v_mfma_f32_16x16x32_bf16 v[126:129], v[134:137], v[190:193], v[126:129]
	v_mfma_f32_16x16x32_bf16 v[92:95], v[142:145], v[190:193], v[92:95]
	v_mfma_f32_16x16x32_bf16 v[122:125], v[134:137], v[230:233], v[122:125]
	v_mfma_f32_16x16x32_bf16 v[88:91], v[142:145], v[230:233], v[88:91]
	v_mfma_f32_16x16x32_bf16 v[106:109], v[134:137], v[238:241], v[106:109]
	v_mfma_f32_16x16x32_bf16 v[72:75], v[142:145], v[238:241], v[72:75]
	s_setprio 0
	s_setprio 1
	v_mfma_f32_16x16x32_bf16 v[102:105], v[158:161], v[174:177], v[102:105]
	v_mfma_f32_16x16x32_bf16 v[64:67], v[166:169], v[174:177], v[64:67]
	v_mfma_f32_16x16x32_bf16 v[118:121], v[158:161], v[186:189], v[118:121]
	v_mfma_f32_16x16x32_bf16 v[84:87], v[166:169], v[186:189], v[84:87]
	v_mfma_f32_16x16x32_bf16 v[114:117], v[158:161], v[226:229], v[114:117]
	v_mfma_f32_16x16x32_bf16 v[80:83], v[166:169], v[226:229], v[80:83]
	v_mfma_f32_16x16x32_bf16 v[98:101], v[158:161], v[234:237], v[98:101]
	v_mfma_f32_16x16x32_bf16 v[68:71], v[166:169], v[234:237], v[68:71]
	v_mfma_f32_16x16x32_bf16 v[102:105], v[162:165], v[178:181], v[102:105]
	v_mfma_f32_16x16x32_bf16 v[64:67], v[170:173], v[178:181], v[64:67]
	v_mfma_f32_16x16x32_bf16 v[118:121], v[162:165], v[190:193], v[118:121]
	v_mfma_f32_16x16x32_bf16 v[84:87], v[170:173], v[190:193], v[84:87]
	v_mfma_f32_16x16x32_bf16 v[114:117], v[162:165], v[230:233], v[114:117]
	v_mfma_f32_16x16x32_bf16 v[80:83], v[170:173], v[230:233], v[80:83]
	v_mfma_f32_16x16x32_bf16 v[98:101], v[162:165], v[238:241], v[98:101]
	v_mfma_f32_16x16x32_bf16 v[68:71], v[170:173], v[238:241], v[68:71]
	s_setprio 0
	s_barrier
	s_add_i32 s29, s29, s69
	v_lshl_add_u64 v[194:195], s[10:11], 0, v[150:151]
	s_mov_b32 m0, s29
	ds_read_b128 v[174:177], v185 offset:16384
	ds_read_b128 v[178:181], v185 offset:17408
	ds_read_b128 v[186:189], v185 offset:18432
	ds_read_b128 v[190:193], v185 offset:19456
	ds_read_b128 v[226:229], v185 offset:20480
	ds_read_b128 v[230:233], v185 offset:21504
	ds_read_b128 v[234:237], v185 offset:22528
	ds_read_b128 v[238:241], v185 offset:23552
	global_load_lds_dwordx4 v[194:195], off
	s_add_i32 m0, s29, 0x2000
	s_add_u32 s36, s10, 0x580000
	v_lshl_add_u64 v[198:199], s[10:11], 0, v[146:147]
	s_addc_u32 s37, s11, 0
	s_add_i32 s29, s38, s69
	global_load_lds_dwordx4 v[198:199], off
	v_lshl_add_u64 v[202:203], s[36:37], 0, v[150:151]
	s_mov_b32 m0, s29
	v_lshl_add_u64 v[204:205], s[12:13], 0, v[148:149]
	global_load_lds_dwordx4 v[202:203], off
	v_lshl_add_u64 v[202:203], s[36:37], 0, v[146:147]
	s_add_i32 m0, s29, 0x2000
	s_nop 0
	global_load_lds_dwordx4 v[202:203], off
	v_lshl_add_u64 v[202:203], s[12:13], 0, v[152:153]
	s_mov_b32 m0, s85
	s_nop 0
	global_load_lds_dwordx4 v[202:203], off
	s_mov_b32 m0, s86
	s_nop 0
	global_load_lds_dwordx4 v[204:205], off
	s_waitcnt vmcnt(8)
	s_waitcnt lgkmcnt(0)
	s_barrier
; #define PG8_STAGE(bufoff, gbase, voff) do { _Pragma("unroll") for (int _i = 0; _i < 2; ++_i) \
;         __builtin_amdgcn_global_load_lds((const unsigned*)((const char*)(gbase) + (voff)[_i]), (LAS unsigned*)(lds + (bufoff) + ldsw + _i * 8192), 16, 0, 0); } while (0)
; #define PG8_LDA(dst, b, h) do { _Pragma("unroll") for (int m = 0; m < 4; ++m) _Pragma("unroll") for (int k = 0; k < 2; ++k) dst[m][k] = *(const LAS bf16x8*)(lds + PG8_SA(b, h) + aoff + m * 2048 + k * 1024); } while (0)
; #define PG8_LDB(dst, b, h) do { _Pragma("unroll") for (int n = 0; n < 2; ++n) _Pragma("unroll") for (int k = 0; k < 2; ++k) dst[n][k] = *(const LAS bf16x8*)(lds + PG8_SB(b, h) + boff + n * 2048 + k * 1024); } while (0)
; #define PG8_MMA(ai, bj, At, Bt) do { __builtin_amdgcn_s_setprio(1); _Pragma("unroll") for (int m = 0; m < 4; ++m) _Pragma("unroll") for (int n = 0; n < 2; ++n) _Pragma("unroll") for (int k = 0; k < 2; ++k) \
;         acc[ai][bj][m][n] = __builtin_amdgcn_mfma_f32_16x16x32_bf16(Bt[n][k], At[m][k], acc[ai][bj][m][n], 0, 0, 0); __builtin_amdgcn_s_setprio(0); } while (0)
; #define PG8_WAIT_V(n) asm volatile("s_waitcnt vmcnt(" #n ")" ::: "memory")
; #define PG8_WAIT_L(n) asm volatile("s_waitcnt lgkmcnt(" #n ")" ::: "memory")
; #define PG8_BAR __builtin_amdgcn_s_barrier()
; #define PG8_SCHED __builtin_amdgcn_sched_barrier(0)
; template <class Epi>
; __device__ __forceinline__ void gemm_phase(ldsp lds, const Gemm g, const StaticOrder& S, const Epi& E, const int tid) {
;     ...
;             PG8_WAIT_V(8); PG8_WAIT_L(0); PG8_BAR; PG8_MMA(0, 0, At, B0); PG8_MMA(0, 1, At, B1); PG8_BAR; PG8_SCHED;
;             PG8_LDA(At, 0, 1); PG8_STAGE(PG8_SB(0, 0), b2, voffB); PG8_STAGE(PG8_SB(0, 1), b2 + hstepB, voffB); PG8_STAGE(PG8_SA(0, 0), a2, voffA);
;             PG8_WAIT_V(8); PG8_WAIT_L(0); PG8_BAR; PG8_MMA(1, 0, At, B0); PG8_MMA(1, 1, At, B1); PG8_BAR; PG8_SCHED;
;             PG8_LDB(B0, 1, 0); PG8_LDB(B1, 1, 1); PG8_SCHED; PG8_LDA(At, 1, 0); PG8_STAGE(PG8_SA(0, 1), a2 + hstepA, voffA);
;             PG8_WAIT_V(8); PG8_WAIT_L(0); PG8_BAR; PG8_MMA(0, 0, At, B0); PG8_MMA(0, 1, At, B1); PG8_BAR; PG8_SCHED;
	s_setprio 1
	s_waitcnt lgkmcnt(0)
	v_mfma_f32_16x16x32_bf16 v[44:47], v[130:133], v[174:177], v[44:47]
	v_mfma_f32_16x16x32_bf16 v[0:3], v[138:141], v[174:177], v[0:3]
	v_mfma_f32_16x16x32_bf16 v[60:63], v[130:133], v[186:189], v[60:63]
	v_mfma_f32_16x16x32_bf16 v[28:31], v[138:141], v[186:189], v[28:31]
	v_mfma_f32_16x16x32_bf16 v[56:59], v[130:133], v[226:229], v[56:59]
	v_mfma_f32_16x16x32_bf16 v[24:27], v[138:141], v[226:229], v[24:27]
	v_mfma_f32_16x16x32_bf16 v[40:43], v[130:133], v[234:237], v[40:43]
	v_mfma_f32_16x16x32_bf16 v[4:7], v[138:141], v[234:237], v[4:7]
	v_mfma_f32_16x16x32_bf16 v[44:47], v[134:137], v[178:181], v[44:47]
	v_mfma_f32_16x16x32_bf16 v[0:3], v[142:145], v[178:181], v[0:3]
	v_mfma_f32_16x16x32_bf16 v[60:63], v[134:137], v[190:193], v[60:63]
	v_mfma_f32_16x16x32_bf16 v[28:31], v[142:145], v[190:193], v[28:31]
	v_mfma_f32_16x16x32_bf16 v[56:59], v[134:137], v[230:233], v[56:59]
	v_mfma_f32_16x16x32_bf16 v[24:27], v[142:145], v[230:233], v[24:27]
	v_mfma_f32_16x16x32_bf16 v[40:43], v[134:137], v[238:241], v[40:43]
	v_mfma_f32_16x16x32_bf16 v[4:7], v[142:145], v[238:241], v[4:7]
	s_setprio 0
	s_setprio 1
	v_mfma_f32_16x16x32_bf16 v[36:39], v[158:161], v[174:177], v[36:39]
	v_mfma_f32_16x16x32_bf16 v[8:11], v[166:169], v[174:177], v[8:11]
	v_mfma_f32_16x16x32_bf16 v[52:55], v[158:161], v[186:189], v[52:55]
	v_mfma_f32_16x16x32_bf16 v[20:23], v[166:169], v[186:189], v[20:23]
	v_mfma_f32_16x16x32_bf16 v[48:51], v[158:161], v[226:229], v[48:51]
	v_mfma_f32_16x16x32_bf16 v[16:19], v[166:169], v[226:229], v[16:19]
	v_mfma_f32_16x16x32_bf16 v[32:35], v[158:161], v[234:237], v[32:35]
	v_mfma_f32_16x16x32_bf16 v[12:15], v[166:169], v[234:237], v[12:15]
	v_mfma_f32_16x16x32_bf16 v[36:39], v[162:165], v[178:181], v[36:39]
	v_mfma_f32_16x16x32_bf16 v[8:11], v[170:173], v[178:181], v[8:11]
	v_mfma_f32_16x16x32_bf16 v[52:55], v[162:165], v[190:193], v[52:55]
	v_mfma_f32_16x16x32_bf16 v[20:23], v[170:173], v[190:193], v[20:23]
	v_mfma_f32_16x16x32_bf16 v[48:51], v[162:165], v[230:233], v[48:51]
	v_mfma_f32_16x16x32_bf16 v[16:19], v[170:173], v[230:233], v[16:19]
	v_mfma_f32_16x16x32_bf16 v[32:35], v[162:165], v[238:241], v[32:35]
	v_mfma_f32_16x16x32_bf16 v[12:15], v[170:173], v[238:241], v[12:15]
	s_setprio 0
	s_barrier
	s_add_i32 s29, 0, 0x18000
	v_add_u32_e32 v96, s29, v184
	s_add_i32 s36, 0, 0x1c000
	ds_read_b128 v[130:133], v96
	ds_read_b128 v[134:137], v96 offset:1024
	ds_read_b128 v[138:141], v96 offset:2048
	ds_read_b128 v[142:145], v96 offset:3072
	v_add_u32_e32 v96, s36, v184
	ds_read_b128 v[158:161], v96
	ds_read_b128 v[162:165], v96 offset:1024
	ds_read_b128 v[166:169], v96 offset:2048
	ds_read_b128 v[170:173], v96 offset:3072
	s_add_u32 s12, s12, 0x40000
	s_addc_u32 s13, s13, 0
	s_mov_b32 m0, s87
	v_lshl_add_u64 v[206:207], s[12:13], 0, v[152:153]
	ds_read_b128 v[174:177], v185 offset:32768
	ds_read_b128 v[178:181], v185 offset:33792
	ds_read_b128 v[186:189], v185 offset:34816
	ds_read_b128 v[190:193], v185 offset:35840
	ds_read_b128 v[226:229], v185 offset:36864
	ds_read_b128 v[230:233], v185 offset:37888
	ds_read_b128 v[234:237], v185 offset:38912
	ds_read_b128 v[238:241], v185 offset:39936
	global_load_lds_dwordx4 v[206:207], off
	v_lshl_add_u64 v[206:207], s[12:13], 0, v[148:149]
	s_mov_b32 m0, s48
	s_nop 0
	global_load_lds_dwordx4 v[206:207], off
	s_waitcnt vmcnt(8)
	s_waitcnt lgkmcnt(0)
	s_barrier
	s_setprio 1
	s_waitcnt lgkmcnt(0)
	v_mfma_f32_16x16x32_bf16 v[110:113], v[130:133], v[174:177], v[110:113]
	v_mfma_f32_16x16x32_bf16 v[76:79], v[138:141], v[174:177], v[76:79]
	v_mfma_f32_16x16x32_bf16 v[126:129], v[130:133], v[186:189], v[126:129]
	v_mfma_f32_16x16x32_bf16 v[92:95], v[138:141], v[186:189], v[92:95]
	v_mfma_f32_16x16x32_bf16 v[122:125], v[130:133], v[226:229], v[122:125]
	v_mfma_f32_16x16x32_bf16 v[88:91], v[138:141], v[226:229], v[88:91]
	v_mfma_f32_16x16x32_bf16 v[106:109], v[130:133], v[234:237], v[106:109]
	v_mfma_f32_16x16x32_bf16 v[72:75], v[138:141], v[234:237], v[72:75]
	v_mfma_f32_16x16x32_bf16 v[110:113], v[134:137], v[178:181], v[110:113]
	v_mfma_f32_16x16x32_bf16 v[76:79], v[142:145], v[178:181], v[76:79]
	v_mfma_f32_16x16x32_bf16 v[126:129], v[134:137], v[190:193], v[126:129]
	v_mfma_f32_16x16x32_bf16 v[92:95], v[142:145], v[190:193], v[92:95]
	v_mfma_f32_16x16x32_bf16 v[122:125], v[134:137], v[230:233], v[122:125]
	v_mfma_f32_16x16x32_bf16 v[88:91], v[142:145], v[230:233], v[88:91]
	v_mfma_f32_16x16x32_bf16 v[106:109], v[134:137], v[238:241], v[106:109]
	v_mfma_f32_16x16x32_bf16 v[72:75], v[142:145], v[238:241], v[72:75]
	s_setprio 0
	s_setprio 1
	v_mfma_f32_16x16x32_bf16 v[102:105], v[158:161], v[174:177], v[102:105]
	v_mfma_f32_16x16x32_bf16 v[64:67], v[166:169], v[174:177], v[64:67]
	v_mfma_f32_16x16x32_bf16 v[118:121], v[158:161], v[186:189], v[118:121]
	v_mfma_f32_16x16x32_bf16 v[84:87], v[166:169], v[186:189], v[84:87]
	v_mfma_f32_16x16x32_bf16 v[114:117], v[158:161], v[226:229], v[114:117]
	v_mfma_f32_16x16x32_bf16 v[80:83], v[166:169], v[226:229], v[80:83]
	v_mfma_f32_16x16x32_bf16 v[98:101], v[158:161], v[234:237], v[98:101]
	v_mfma_f32_16x16x32_bf16 v[68:71], v[166:169], v[234:237], v[68:71]
	v_mfma_f32_16x16x32_bf16 v[102:105], v[162:165], v[178:181], v[102:105]
	v_mfma_f32_16x16x32_bf16 v[64:67], v[170:173], v[178:181], v[64:67]
	v_mfma_f32_16x16x32_bf16 v[118:121], v[162:165], v[190:193], v[118:121]
	v_mfma_f32_16x16x32_bf16 v[84:87], v[170:173], v[190:193], v[84:87]
	v_mfma_f32_16x16x32_bf16 v[114:117], v[162:165], v[230:233], v[114:117]
	v_mfma_f32_16x16x32_bf16 v[80:83], v[170:173], v[230:233], v[80:83]
	v_mfma_f32_16x16x32_bf16 v[98:101], v[162:165], v[238:241], v[98:101]
	v_mfma_f32_16x16x32_bf16 v[68:71], v[170:173], v[238:241], v[68:71]
	s_setprio 0
	s_barrier
; #define PG8_STAGE(bufoff, gbase, voff) do { _Pragma("unroll") for (int _i = 0; _i < 2; ++_i) \
;         __builtin_amdgcn_global_load_lds((const unsigned*)((const char*)(gbase) + (voff)[_i]), (LAS unsigned*)(lds + (bufoff) + ldsw + _i * 8192), 16, 0, 0); } while (0)
; #define PG8_LDA(dst, b, h) do { _Pragma("unroll") for (int m = 0; m < 4; ++m) _Pragma("unroll") for (int k = 0; k < 2; ++k) dst[m][k] = *(const LAS bf16x8*)(lds + PG8_SA(b, h) + aoff + m * 2048 + k * 1024); } while (0)
; #define PG8_MMA(ai, bj, At, Bt) do { __builtin_amdgcn_s_setprio(1); _Pragma("unroll") for (int m = 0; m < 4; ++m) _Pragma("unroll") for (int n = 0; n < 2; ++n) _Pragma("unroll") for (int k = 0; k < 2; ++k) \
;         acc[ai][bj][m][n] = __builtin_amdgcn_mfma_f32_16x16x32_bf16(Bt[n][k], At[m][k], acc[ai][bj][m][n], 0, 0, 0); __builtin_amdgcn_s_setprio(0); } while (0)
; #define PG8_WAIT_V(n) asm volatile("s_waitcnt vmcnt(" #n ")" ::: "memory")
; #define PG8_WAIT_L(n) asm volatile("s_waitcnt lgkmcnt(" #n ")" ::: "memory")
; #define PG8_BAR __builtin_amdgcn_s_barrier()
; #define PG8_SCHED __builtin_amdgcn_sched_barrier(0)
;     __device__ __forceinline__ void operator()(const f32x4 (&acc)[2][2][4][2], const Unit& u, int wr, int wc, int fr_in, int fq_in) const {
;     ...
;                     const f32x4 k0 = *(const f32x4*)(fk + co + ch), k1 = *(const f32x4*)(fk + DFF2 + co + ch), k2 = *(const f32x4*)(fk + 2 * DFF2 + co + ch), bb = *(const f32x4*)(fb + co + ch);
; template <class Epi>
; __device__ __forceinline__ void gemm_phase(ldsp lds, const Gemm g, const StaticOrder& S, const Epi& E, const int tid) {
;     ...
;             PG8_WAIT_V(8); PG8_WAIT_L(0); PG8_BAR; PG8_MMA(0, 0, At, B0); PG8_MMA(0, 1, At, B1); PG8_BAR; PG8_SCHED;
;             PG8_LDA(At, 1, 1); PG8_STAGE(PG8_SB(1, 0), b3, voffB); PG8_STAGE(PG8_SB(1, 1), b3 + hstepB, voffB); PG8_STAGE(PG8_SA(1, 0), a3, voffA);
;             PG8_WAIT_V(8); PG8_WAIT_L(0); PG8_BAR; PG8_MMA(1, 0, At, B0); PG8_MMA(1, 1, At, B1); PG8_BAR; PG8_SCHED;
;         }
;         if (wr == 0) PG8_BAR;
	s_add_i32 s12, s29, s69
	v_lshl_add_u64 v[194:195], v[194:195], 0, s[50:51]
	s_mov_b32 m0, s12
	ds_read_b128 v[174:177], v185 offset:49152
	ds_read_b128 v[178:181], v185 offset:50176
	ds_read_b128 v[186:189], v185 offset:51200
	ds_read_b128 v[190:193], v185 offset:52224
	ds_read_b128 v[226:229], v185 offset:53248
	ds_read_b128 v[230:233], v185 offset:54272
	ds_read_b128 v[234:237], v185 offset:55296
	ds_read_b128 v[238:241], v185 offset:56320
	global_load_lds_dwordx4 v[194:195], off
	s_add_i32 m0, s12, 0x2000
	s_add_u32 s10, s10, 0x580080
	v_lshl_add_u64 v[194:195], v[198:199], 0, s[50:51]
	s_addc_u32 s11, s11, 0
	s_add_i32 s12, s36, s69
	global_load_lds_dwordx4 v[194:195], off
	v_lshl_add_u64 v[194:195], s[10:11], 0, v[150:151]
	s_mov_b32 m0, s12
	s_nop 0
	global_load_lds_dwordx4 v[194:195], off
	v_lshl_add_u64 v[194:195], s[10:11], 0, v[146:147]
	s_add_i32 m0, s12, 0x2000
	s_nop 0
	global_load_lds_dwordx4 v[194:195], off
	v_lshl_add_u64 v[194:195], v[202:203], 0, s[50:51]
	s_mov_b32 m0, s15
	s_nop 0
	global_load_lds_dwordx4 v[194:195], off
	v_lshl_add_u64 v[194:195], v[204:205], 0, s[50:51]
	s_mov_b32 m0, s16
	s_nop 0
	global_load_lds_dwordx4 v[194:195], off
	s_waitcnt vmcnt(8)
	s_waitcnt lgkmcnt(0)
	s_barrier
	s_setprio 1
	s_waitcnt lgkmcnt(0)
	v_mfma_f32_16x16x32_bf16 v[44:47], v[130:133], v[174:177], v[44:47]
	v_mfma_f32_16x16x32_bf16 v[0:3], v[138:141], v[174:177], v[0:3]
	v_mfma_f32_16x16x32_bf16 v[60:63], v[130:133], v[186:189], v[60:63]
	v_mfma_f32_16x16x32_bf16 v[28:31], v[138:141], v[186:189], v[28:31]
	v_mfma_f32_16x16x32_bf16 v[56:59], v[130:133], v[226:229], v[56:59]
	v_mfma_f32_16x16x32_bf16 v[24:27], v[138:141], v[226:229], v[24:27]
	v_mfma_f32_16x16x32_bf16 v[40:43], v[130:133], v[234:237], v[40:43]
	v_mfma_f32_16x16x32_bf16 v[4:7], v[138:141], v[234:237], v[4:7]
	v_mfma_f32_16x16x32_bf16 v[44:47], v[134:137], v[178:181], v[44:47]
	v_mfma_f32_16x16x32_bf16 v[0:3], v[142:145], v[178:181], v[0:3]
	v_mfma_f32_16x16x32_bf16 v[60:63], v[134:137], v[190:193], v[60:63]
	v_mfma_f32_16x16x32_bf16 v[28:31], v[142:145], v[190:193], v[28:31]
	v_mfma_f32_16x16x32_bf16 v[56:59], v[134:137], v[230:233], v[56:59]
	v_mfma_f32_16x16x32_bf16 v[24:27], v[142:145], v[230:233], v[24:27]
	v_mfma_f32_16x16x32_bf16 v[40:43], v[134:137], v[238:241], v[40:43]
	v_mfma_f32_16x16x32_bf16 v[4:7], v[142:145], v[238:241], v[4:7]
	s_setprio 0
	s_setprio 1
	v_mfma_f32_16x16x32_bf16 v[36:39], v[158:161], v[174:177], v[36:39]
	v_mfma_f32_16x16x32_bf16 v[8:11], v[166:169], v[174:177], v[8:11]
	v_mfma_f32_16x16x32_bf16 v[52:55], v[158:161], v[186:189], v[52:55]
	v_mfma_f32_16x16x32_bf16 v[20:23], v[166:169], v[186:189], v[20:23]
	v_mfma_f32_16x16x32_bf16 v[48:51], v[158:161], v[226:229], v[48:51]
	v_mfma_f32_16x16x32_bf16 v[16:19], v[166:169], v[226:229], v[16:19]
	v_mfma_f32_16x16x32_bf16 v[32:35], v[158:161], v[234:237], v[32:35]
	v_mfma_f32_16x16x32_bf16 v[12:15], v[166:169], v[234:237], v[12:15]
	v_mfma_f32_16x16x32_bf16 v[36:39], v[162:165], v[178:181], v[36:39]
	v_mfma_f32_16x16x32_bf16 v[8:11], v[170:173], v[178:181], v[8:11]
	v_mfma_f32_16x16x32_bf16 v[52:55], v[162:165], v[190:193], v[52:55]
	v_mfma_f32_16x16x32_bf16 v[20:23], v[170:173], v[190:193], v[20:23]
	v_mfma_f32_16x16x32_bf16 v[48:51], v[162:165], v[230:233], v[48:51]
	v_mfma_f32_16x16x32_bf16 v[16:19], v[170:173], v[230:233], v[16:19]
	v_mfma_f32_16x16x32_bf16 v[32:35], v[162:165], v[238:241], v[32:35]
	v_mfma_f32_16x16x32_bf16 v[12:15], v[170:173], v[238:241], v[12:15]
	s_setprio 0
	s_barrier
	s_add_i32 s27, s27, 2
	s_add_u32 s6, s6, 0x100
	s_addc_u32 s7, s7, 0
	s_add_u32 s22, s22, 0x100
	s_addc_u32 s23, s23, 0
	s_cmp_gt_u32 s27, 13
	s_cbranch_scc0 .LBB0_1043
	v_and_b32_e32 v214, 63, v196
	v_lshrrev_b32_e32 v96, 6, v196
	v_bfe_u32 v130, v214, 2, 2
	v_bfe_u32 v131, v214, 4, 1
	v_lshrrev_b32_e32 v213, 5, v214
	v_and_b32_e32 v214, 3, v214
	v_readfirstlane_b32 s100, v96
	s_lshl_b32 s101, s8, 7
	s_or_b32 s101, s101, s14
	v_lshl_add_u32 v214, v214, 3, s101
	v_lshl_add_u32 v214, v213, 2, v214
	v_lshlrev_b32_e32 v214, 2, v214
	v_mul_u32_u24_e32 v131, 0x2c00, v131
	v_add_u32_e32 v214, v214, v131
	v_cmp_eq_u32_e32 vcc, 3, v130
	v_mul_u32_u24_e32 v130, 0x5800, v130
	v_mov_b32_e32 v131, s53
	v_mov_b32_e32 v96, s54
	v_cndmask_b32_e64 v130, v130, 0, vcc
	v_add_u32_e32 v214, v214, v130
	v_mov_b32_e32 v130, s52
	v_cndmask_b32_e32 v130, v130, v96, vcc
	v_mov_b32_e32 v96, s55
	v_cndmask_b32_e32 v131, v131, v96, vcc
	v_add_co_u32_e32 v214, vcc, v130, v214
	s_lshl_b32 s100, s100, 10
	s_add_i32 s100, s100, 0x20000
	v_addc_co_u32_e32 v215, vcc, 0, v131, vcc
	s_mov_b32 m0, s100
	v_lshl_add_u32 v213, v183, 4, s100
	global_load_lds_dwordx4 v[214:215], off
	s_and_b64 vcc, exec, s[58:59]
	s_cbranch_vccz .LBB0_1046
	s_barrier
; #define DPP_UP(v) __int_as_float(__builtin_amdgcn_update_dpp(0, __float_as_int(v), 0x121, 0xf, 0xf, false))
; #define DPP_DN(v) __int_as_float(__builtin_amdgcn_update_dpp(0, __float_as_int(v), 0x12F, 0xf, 0xf, false))
;     __device__ __forceinline__ void operator()(const f32x4 (&acc)[2][2][4][2], const Unit& u, int wr, int wc, int fr_in, int fq_in) const {
;         const int fr0_ = fr_in, fq0_ = fq_in;
;         char* base = (char*)(A2 + (size_t)(u.pm * BM) * DFF);
;         char* sbase = (char*)(side + (size_t)(u.pm * 16) * DFF2);
;         int fr_l = fr0_, fq_l = fq0_; asm volatile("" : "+v"(fr_l), "+v"(fq_l));
;         const int fr = fr_l, fq = fq_l;
;         const int ch0 = u.pn * HALF + wc * 32 + 8 * fq;
;         const unsigned off0 = (unsigned)(wr * 64 + fr) * (DFF * 2u) + (unsigned)ch0 * 2u;
;         const bool f0 = fr == 0, f15 = fr == 15;
;     ...
; #pragma unroll
;         for (int ai = 0; ai < 2; ++ai) {
;             f32x4 o[4]; u32x2 wlo[4];
; #pragma unroll
;             for (int n = 0; n < 2; ++n) {
;                 const int ch = ch0 + 4 * n;
; #pragma unroll
;                 for (int pass = 0; pass < 2; ++pass) {
;                     const int co = pass ? DFF : 0;
;                     const f32x4 k0 = *(const f32x4*)(fk + co + ch), k1 = *(const f32x4*)(fk + DFF2 + co + ch), k2 = *(const f32x4*)(fk + 2 * DFF2 + co + ch), bb = *(const f32x4*)(fb + co + ch);
;                     f32x4 up_prev = (f32x4){0.f, 0.f, 0.f, 0.f}, up_cur, dn_cur, dn_next;
; #pragma unroll
;                     for (int j = 0; j < 4; ++j) dn_cur[j] = DPP_DN(acc[ai][pass][0][n][j]);
; #pragma unroll
;                     for (int m = 0; m < 4; ++m) {
;                         const f32x4 xv = acc[ai][pass][m][n];
; #pragma unroll
;                         for (int j = 0; j < 4; ++j) { up_cur[j] = DPP_UP(xv[j]); dn_next[j] = (m < 3) ? DPP_DN(acc[ai][pass][m < 3 ? m + 1 : 3][n][j]) : 0.f; }
;                         const f32x4 xp = f0 ? up_prev : up_cur, xn = f15 ? dn_next : dn_cur;
;                         const f32x4 c = (k0 * xp + k1 * xv) + (k2 * xn + bb);
.LBB0_1046:
	s_lshl_b32 s0, s42, 4
	s_mul_i32 s1, s42, 0x2c000
	s_mul_hi_i32 s0, s0, 0x2c00
	s_add_u32 s40, s46, s1
	s_addc_u32 s41, s64, s0
	v_mov_b32_e32 v96, v182
	v_mov_b32_e32 v130, v183
	s_lshl_b32 s0, s8, 7
	s_or_b32 s0, s0, s14
	v_lshl_add_u32 v158, v130, 3, s0
	v_add_u32_e32 v130, -14, v96
	v_cmp_gt_u32_e64 s[8:9], -12, v130
	v_cmp_gt_i32_e64 s[6:7], 2, v96
	v_add_u32_e32 v130, -12, v96
	v_ashrrev_i32_e32 v159, 31, v158
	v_cndmask_b32_e64 v130, v130, v96, s[6:7]
	v_add_u32_e32 v186, s17, v130
	v_mov_b64_e32 v[130:131], s[40:41]
	v_mad_i64_i32 v[166:167], s[0:1], v186, s45, v[130:131]
	v_lshlrev_b64 v[130:131], 2, v[158:159]
	v_lshl_add_u64 v[160:161], s[52:53], 0, v[130:131]
	v_lshl_add_u64 v[168:169], s[90:91], 0, v[130:131]
	v_lshl_add_u64 v[164:165], s[92:93], 0, v[130:131]
	v_lshl_add_u64 v[162:163], s[54:55], 0, v[130:131]
	s_waitcnt vmcnt(0)
	ds_read_b128 v[134:137], v213 offset:0
	ds_read_b128 v[130:133], v213 offset:64
	ds_read_b128 v[138:141], v213 offset:128
	ds_read_b128 v[142:145], v213 offset:192
	v_mov_b32_e32 v170, v97
	v_mov_b32_e32 v171, v97
	v_mov_b32_e32 v179, v97
	v_mov_b32_e32 v181, v97
	v_cmp_eq_u32_e64 s[12:13], 15, v96
	v_mov_b32_dpp v170, v110 row_ror:15 row_mask:0xf bank_mask:0xf
	v_mov_b32_dpp v171, v111 row_ror:15 row_mask:0xf bank_mask:0xf
	v_mov_b32_e32 v178, v97
	v_mov_b32_dpp v179, v126 row_ror:15 row_mask:0xf bank_mask:0xf
	v_mov_b32_e32 v180, v97
	v_mov_b32_dpp v181, v127 row_ror:15 row_mask:0xf bank_mask:0xf
	v_mov_b32_e32 v187, v97
	v_mov_b32_e32 v189, v97
	v_cmp_eq_u32_e64 s[10:11], 0, v96
	v_mov_b32_e32 v172, v97
	v_mov_b32_e32 v173, v97
	v_mov_b32_dpp v178, v110 row_ror:1 row_mask:0xf bank_mask:0xf
	v_mov_b32_dpp v180, v111 row_ror:1 row_mask:0xf bank_mask:0xf
	v_mov_b32_dpp v187, v112 row_ror:1 row_mask:0xf bank_mask:0xf
	v_mov_b32_e32 v188, v97
	v_mov_b32_dpp v189, v113 row_ror:1 row_mask:0xf bank_mask:0xf
	v_mov_b32_e32 v190, v97
	v_cndmask_b32_e64 v171, v171, v181, s[12:13]
	v_cndmask_b32_e64 v170, v170, v179, s[12:13]
	v_mov_b32_dpp v172, v112 row_ror:15 row_mask:0xf bank_mask:0xf
	v_mov_b32_dpp v173, v113 row_ror:15 row_mask:0xf bank_mask:0xf
	v_mov_b32_dpp v188, v128 row_ror:15 row_mask:0xf bank_mask:0xf
	v_mov_b32_dpp v190, v129 row_ror:15 row_mask:0xf bank_mask:0xf
	v_cndmask_b32_e64 v177, v180, 0, s[10:11]
	v_cndmask_b32_e64 v176, v178, 0, s[10:11]
	v_cndmask_b32_e64 v173, v173, v190, s[12:13]
	v_cndmask_b32_e64 v172, v172, v188, s[12:13]
	v_mov_b32_e32 v192, v97
	v_mov_b32_e32 v193, v97
	v_mov_b32_e32 v194, v97
	v_mov_b32_e32 v195, v97
	v_mov_b32_e32 v198, v97
	v_mov_b32_e32 v191, v97
	v_mov_b32_dpp v192, v122 row_ror:15 row_mask:0xf bank_mask:0xf
	v_mov_b32_dpp v193, v127 row_ror:1 row_mask:0xf bank_mask:0xf
	v_mov_b32_dpp v194, v123 row_ror:15 row_mask:0xf bank_mask:0xf
	v_mov_b32_dpp v195, v128 row_ror:1 row_mask:0xf bank_mask:0xf
	v_mov_b32_e32 v197, v97
	v_mov_b32_dpp v198, v129 row_ror:1 row_mask:0xf bank_mask:0xf
	v_mov_b32_e32 v199, v97
	v_mov_b32_dpp v191, v126 row_ror:1 row_mask:0xf bank_mask:0xf
	v_mov_b32_dpp v197, v124 row_ror:15 row_mask:0xf bank_mask:0xf
	v_mov_b32_dpp v199, v125 row_ror:15 row_mask:0xf bank_mask:0xf
	v_cndmask_b32_e64 v178, v191, v178, s[10:11]
	v_mov_b32_e32 v200, v97
	v_mov_b32_e32 v203, v97
	v_mov_b32_e32 v202, v97
	v_mov_b32_dpp v200, v124 row_ror:1 row_mask:0xf bank_mask:0xf
	v_mov_b32_dpp v203, v125 row_ror:1 row_mask:0xf bank_mask:0xf
	v_mov_b32_e32 v204, v97
	v_mov_b32_dpp v202, v108 row_ror:15 row_mask:0xf bank_mask:0xf
	v_mov_b32_e32 v205, v97
	v_mov_b32_dpp v204, v109 row_ror:15 row_mask:0xf bank_mask:0xf
	v_mov_b32_e32 v207, v97
	v_mov_b32_dpp v205, v121 row_ror:15 row_mask:0xf bank_mask:0xf
	v_mov_b32_e32 v209, v97
	v_mov_b32_e32 v211, v97
	v_mov_b32_e32 v206, v97
	v_mov_b32_dpp v207, v119 row_ror:1 row_mask:0xf bank_mask:0xf
	v_mov_b32_e32 v208, v97
	v_mov_b32_dpp v209, v120 row_ror:1 row_mask:0xf bank_mask:0xf
	v_mov_b32_e32 v210, v97
	v_mov_b32_dpp v211, v121 row_ror:1 row_mask:0xf bank_mask:0xf
	v_mov_b32_e32 v212, v97
	v_mov_b32_dpp v206, v114 row_ror:15 row_mask:0xf bank_mask:0xf
	v_mov_b32_dpp v208, v115 row_ror:15 row_mask:0xf bank_mask:0xf
	v_mov_b32_dpp v210, v116 row_ror:15 row_mask:0xf bank_mask:0xf
	v_mov_b32_dpp v212, v117 row_ror:15 row_mask:0xf bank_mask:0xf
	s_waitcnt lgkmcnt(0)
; #define DPP_UP(v) __int_as_float(__builtin_amdgcn_update_dpp(0, __float_as_int(v), 0x121, 0xf, 0xf, false))
; #define DPP_DN(v) __int_as_float(__builtin_amdgcn_update_dpp(0, __float_as_int(v), 0x12F, 0xf, 0xf, false))
;     __device__ __forceinline__ void operator()(const f32x4 (&acc)[2][2][4][2], const Unit& u, int wr, int wc, int fr_in, int fq_in) const {
;     ...
;                     const f32x4 k0 = *(const f32x4*)(fk + co + ch), k1 = *(const f32x4*)(fk + DFF2 + co + ch), k2 = *(const f32x4*)(fk + 2 * DFF2 + co + ch), bb = *(const f32x4*)(fb + co + ch);
;                     f32x4 up_prev = (f32x4){0.f, 0.f, 0.f, 0.f}, up_cur, dn_cur, dn_next;
; #pragma unroll
;                     for (int j = 0; j < 4; ++j) dn_cur[j] = DPP_DN(acc[ai][pass][0][n][j]);
; #pragma unroll
;                     for (int m = 0; m < 4; ++m) {
;                         const f32x4 xv = acc[ai][pass][m][n];
; #pragma unroll
;                         for (int j = 0; j < 4; ++j) { up_cur[j] = DPP_UP(xv[j]); dn_next[j] = (m < 3) ? DPP_DN(acc[ai][pass][m < 3 ? m + 1 : 3][n][j]) : 0.f; }
;                         const f32x4 xp = f0 ? up_prev : up_cur, xn = f15 ? dn_next : dn_cur;
;                         const f32x4 c = (k0 * xp + k1 * xv) + (k2 * xn + bb);
;                         if (pass == 0) o[m] = c;
;                         else { f32x4 e;
; #pragma unroll
;                             for (int j = 0; j < 4; ++j) e[j] = __builtin_amdgcn_rcpf(1.0f + __builtin_amdgcn_exp2f(c[j] * -1.4426950408889634f));
;                             o[m] = o[m] * (c * e); }
;                         up_prev = up_cur; dn_cur = dn_next; }
	v_pk_mul_f32 v[176:177], v[134:135], v[176:177]
	s_nop 0
	v_pk_fma_f32 v[176:177], v[110:111], v[130:131], v[176:177]
	v_pk_fma_f32 v[174:175], v[138:139], v[170:171], v[142:143]
	v_cndmask_b32_e64 v171, v189, 0, s[10:11]
	v_cndmask_b32_e64 v170, v187, 0, s[10:11]
	v_pk_mul_f32 v[170:171], v[136:137], v[170:171]
	v_pk_fma_f32 v[172:173], v[140:141], v[172:173], v[144:145]
	v_pk_fma_f32 v[170:171], v[112:113], v[132:133], v[170:171]
	s_nop 0
	v_pk_add_f32 v[170:171], v[170:171], v[172:173]
	v_pk_add_f32 v[172:173], v[176:177], v[174:175]
	v_cndmask_b32_e64 v175, v181, v194, s[12:13]
	v_cndmask_b32_e64 v174, v179, v192, s[12:13]
	v_cndmask_b32_e64 v179, v193, v180, s[10:11]
	v_cndmask_b32_e64 v181, v198, v189, s[10:11]
	v_cndmask_b32_e64 v180, v195, v187, s[10:11]
	v_cndmask_b32_e64 v177, v190, v199, s[12:13]
	v_cndmask_b32_e64 v176, v188, v197, s[12:13]
	v_pk_mul_f32 v[180:181], v[136:137], v[180:181]
	v_pk_fma_f32 v[176:177], v[140:141], v[176:177], v[144:145]
	v_pk_mul_f32 v[178:179], v[134:135], v[178:179]
	v_pk_fma_f32 v[128:129], v[128:129], v[132:133], v[180:181]
	v_mov_b32_e32 v187, v97
	v_mov_b32_e32 v189, v97
	v_pk_fma_f32 v[174:175], v[138:139], v[174:175], v[142:143]
	v_pk_fma_f32 v[126:127], v[126:127], v[130:131], v[178:179]
	v_pk_add_f32 v[178:179], v[128:129], v[176:177]
	v_mov_b32_dpp v187, v122 row_ror:1 row_mask:0xf bank_mask:0xf
	v_mov_b32_dpp v189, v123 row_ror:1 row_mask:0xf bank_mask:0xf
	v_cndmask_b32_e64 v177, v203, v198, s[10:11]
	v_cndmask_b32_e64 v176, v200, v195, s[10:11]
	v_pk_add_f32 v[180:181], v[126:127], v[174:175]
	v_mov_b32_e32 v188, v97
	v_mov_b32_e32 v190, v97
	v_cndmask_b32_e64 v129, v199, v204, s[12:13]
	v_cndmask_b32_e64 v128, v197, v202, s[12:13]
	v_cndmask_b32_e64 v175, v189, v193, s[10:11]
	v_cndmask_b32_e64 v174, v187, v191, s[10:11]
	v_pk_mul_f32 v[176:177], v[136:137], v[176:177]
	v_mov_b32_dpp v188, v106 row_ror:15 row_mask:0xf bank_mask:0xf
	v_mov_b32_dpp v190, v107 row_ror:15 row_mask:0xf bank_mask:0xf
	v_pk_fma_f32 v[128:129], v[140:141], v[128:129], v[144:145]
	v_pk_mul_f32 v[174:175], v[134:135], v[174:175]
	v_pk_fma_f32 v[124:125], v[124:125], v[132:133], v[176:177]
	v_cndmask_b32_e64 v127, v194, v190, s[12:13]
	v_cndmask_b32_e64 v126, v192, v188, s[12:13]
	v_pk_fma_f32 v[122:123], v[122:123], v[130:131], v[174:175]
	v_pk_add_f32 v[174:175], v[124:125], v[128:129]
	v_mov_b32_e32 v128, v97
	v_mov_b32_e32 v129, v97
	v_pk_fma_f32 v[126:127], v[138:139], v[126:127], v[142:143]
	v_mov_b32_dpp v128, v108 row_ror:1 row_mask:0xf bank_mask:0xf
	v_mov_b32_dpp v129, v109 row_ror:1 row_mask:0xf bank_mask:0xf
	v_pk_add_f32 v[176:177], v[122:123], v[126:127]
	v_cndmask_b32_e64 v123, v204, 0, s[12:13]
	v_cndmask_b32_e64 v122, v202, 0, s[12:13]
	v_cndmask_b32_e64 v129, v129, v203, s[10:11]
	v_cndmask_b32_e64 v128, v128, v200, s[10:11]
	v_mov_b32_e32 v126, v97
	v_mov_b32_e32 v127, v97
	v_pk_fma_f32 v[122:123], v[140:141], v[122:123], v[144:145]
	v_pk_mul_f32 v[128:129], v[136:137], v[128:129]
	v_add_co_u32_e32 v140, vcc, s82, v160
	v_mov_b32_dpp v126, v106 row_ror:1 row_mask:0xf bank_mask:0xf
	v_mov_b32_dpp v127, v107 row_ror:1 row_mask:0xf bank_mask:0xf
	v_cndmask_b32_e64 v125, v190, 0, s[12:13]
	v_cndmask_b32_e64 v124, v188, 0, s[12:13]
	v_pk_fma_f32 v[128:129], v[108:109], v[132:133], v[128:129]
	v_addc_co_u32_e32 v141, vcc, 0, v161, vcc
	v_pk_fma_f32 v[124:125], v[138:139], v[124:125], v[142:143]
	v_cndmask_b32_e64 v127, v127, v189, s[10:11]
	v_cndmask_b32_e64 v126, v126, v187, s[10:11]
	v_pk_add_f32 v[142:143], v[122:123], v[128:129]
	v_add_co_u32_e32 v122, vcc, s82, v168
	v_pk_mul_f32 v[126:127], v[134:135], v[126:127]
	s_nop 0
	v_addc_co_u32_e32 v123, vcc, 0, v169, vcc
	v_pk_fma_f32 v[126:127], v[106:107], v[130:131], v[126:127]
	v_add_co_u32_e32 v130, vcc, s82, v164
	v_pk_add_f32 v[144:145], v[124:125], v[126:127]
	s_nop 0
	v_addc_co_u32_e32 v131, vcc, 0, v165, vcc
	v_add_co_u32_e32 v138, vcc, s82, v162
	ds_read_b128 v[126:129], v213 offset:256
	s_nop 0
	v_addc_co_u32_e32 v139, vcc, 0, v163, vcc
	ds_read_b128 v[122:125], v213 offset:320
	v_mov_b32_e32 v197, v97
	ds_read_b128 v[130:133], v213 offset:384
	v_mov_b32_e32 v199, v97
	ds_read_b128 v[134:137], v213 offset:448
	v_mov_b32_e32 v187, v97
	v_mov_b32_e32 v190, v97
	v_mov_b32_dpp v197, v102 row_ror:1 row_mask:0xf bank_mask:0xf
	v_mov_b32_e32 v198, v97
	v_mov_b32_dpp v199, v103 row_ror:1 row_mask:0xf bank_mask:0xf
	v_mov_b32_e32 v200, v97
	v_mov_b32_dpp v187, v102 row_ror:15 row_mask:0xf bank_mask:0xf
	v_mov_b32_dpp v190, v103 row_ror:15 row_mask:0xf bank_mask:0xf
	v_mov_b32_dpp v198, v118 row_ror:15 row_mask:0xf bank_mask:0xf
	v_mov_b32_dpp v200, v119 row_ror:15 row_mask:0xf bank_mask:0xf
	v_cndmask_b32_e64 v193, v199, 0, s[10:11]
	v_cndmask_b32_e64 v192, v197, 0, s[10:11]
	v_cndmask_b32_e64 v191, v190, v200, s[12:13]
	v_cndmask_b32_e64 v190, v187, v198, s[12:13]
	v_mov_b32_e32 v202, v97
	v_mov_b32_e32 v204, v97
	v_mov_b32_e32 v188, v97
	v_mov_b32_e32 v189, v97
	v_mov_b32_dpp v202, v104 row_ror:1 row_mask:0xf bank_mask:0xf
	v_mov_b32_e32 v203, v97
	v_mov_b32_dpp v204, v105 row_ror:1 row_mask:0xf bank_mask:0xf
	v_mov_b32_dpp v188, v104 row_ror:15 row_mask:0xf bank_mask:0xf
	v_mov_b32_dpp v189, v105 row_ror:15 row_mask:0xf bank_mask:0xf
	v_mov_b32_dpp v203, v120 row_ror:15 row_mask:0xf bank_mask:0xf
	v_cndmask_b32_e64 v195, v204, 0, s[10:11]
	v_cndmask_b32_e64 v194, v202, 0, s[10:11]
	v_cndmask_b32_e64 v189, v189, v205, s[12:13]
	v_cndmask_b32_e64 v188, v188, v203, s[12:13]
	s_waitcnt lgkmcnt(3)
	v_pk_mul_f32 v[192:193], v[126:127], v[192:193]
	v_pk_mul_f32 v[194:195], v[128:129], v[194:195]
	s_waitcnt lgkmcnt(2)
; __device__ __forceinline__ unsigned cvt_pk_bf16(float lo, float hi) { unsigned r; asm volatile("v_cvt_pk_bf16_f32 %0, %1, %2" : "=v"(r) : "v"(lo), "v"(hi)); return r; }
; #define DPP_UP(v) __int_as_float(__builtin_amdgcn_update_dpp(0, __float_as_int(v), 0x121, 0xf, 0xf, false))
; #define DPP_DN(v) __int_as_float(__builtin_amdgcn_update_dpp(0, __float_as_int(v), 0x12F, 0xf, 0xf, false))
;     __device__ __forceinline__ void operator()(const f32x4 (&acc)[2][2][4][2], const Unit& u, int wr, int wc, int fr_in, int fq_in) const {
;     ...
;                         for (int j = 0; j < 4; ++j) { up_cur[j] = DPP_UP(xv[j]); dn_next[j] = (m < 3) ? DPP_DN(acc[ai][pass][m < 3 ? m + 1 : 3][n][j]) : 0.f; }
;                         const f32x4 xp = f0 ? up_prev : up_cur, xn = f15 ? dn_next : dn_cur;
;                         const f32x4 c = (k0 * xp + k1 * xv) + (k2 * xn + bb);
;                         if (pass == 0) o[m] = c;
;                         else { f32x4 e;
; #pragma unroll
;                             for (int j = 0; j < 4; ++j) e[j] = __builtin_amdgcn_rcpf(1.0f + __builtin_amdgcn_exp2f(c[j] * -1.4426950408889634f));
;                             o[m] = o[m] * (c * e); }
;                         up_prev = up_cur; dn_cur = dn_next; }
;                 }
;                 if (n == 0) {
; #pragma unroll
;                     for (int m = 0; m < 4; ++m) { wlo[m].x = cvt_pk_bf16(o[m][0], o[m][1]); wlo[m].y = cvt_pk_bf16(o[m][2], o[m][3]); }
;                 } else {
; #pragma unroll
;                     for (int m = 0; m < 4; ++m) { u32x4 w; w.x = wlo[m].x; w.y = wlo[m].y; w.z = cvt_pk_bf16(o[m][0], o[m][1]); w.w = cvt_pk_bf16(o[m][2], o[m][3]);
;                         *(u32x4*)(base + off0 + (unsigned)(ai * HALF + m * 16) * (DFF * 2u)) = w; }
;                 }
;                 if (fr < 2 || fr >= 14) { const int k = fr < 2 ? fr : fr - 12;
;                     const f32x4 xv = fr < 2 ? acc[ai][0][0][n] : acc[ai][0][3][n], yv = fr < 2 ? acc[ai][1][0][n] : acc[ai][1][3][n];
;                     char* sp = sbase + (size_t)((2 * ai + wr) * 4 + k) * (DFF2 * 2) + (size_t)ch * 2;
;                     u32x2 a, b; a.x = cvt_pk_bf16(xv[0], xv[1]); a.y = cvt_pk_bf16(xv[2], xv[3]); b.x = cvt_pk_bf16(yv[0], yv[1]); b.y = cvt_pk_bf16(yv[2], yv[3]);
	v_pk_fma_f32 v[192:193], v[102:103], v[122:123], v[192:193]
	v_pk_fma_f32 v[194:195], v[104:105], v[124:125], v[194:195]
	s_waitcnt lgkmcnt(0)
	v_pk_fma_f32 v[190:191], v[130:131], v[190:191], v[134:135]
	s_nop 0
	v_pk_add_f32 v[190:191], v[192:193], v[190:191]
	v_pk_fma_f32 v[188:189], v[132:133], v[188:189], v[136:137]
	v_mul_f32_e32 v187, 0xbfb8aa3b, v190
	v_exp_f32_e32 v187, v187
	v_pk_add_f32 v[188:189], v[194:195], v[188:189]
	v_add_f32_e32 v187, 1.0, v187
	v_rcp_f32_e32 v192, v187
	v_mul_f32_e32 v187, 0xbfb8aa3b, v191
	v_exp_f32_e32 v187, v187
	s_nop 0
	v_add_f32_e32 v187, 1.0, v187
	v_rcp_f32_e32 v193, v187
	v_mul_f32_e32 v187, 0xbfb8aa3b, v188
	v_exp_f32_e32 v187, v187
	v_pk_mul_f32 v[190:191], v[190:191], v[192:193]
	v_cndmask_b32_e64 v193, v211, v204, s[10:11]
	v_add_f32_e32 v187, 1.0, v187
	v_rcp_f32_e32 v194, v187
	v_mul_f32_e32 v187, 0xbfb8aa3b, v189
	v_exp_f32_e32 v187, v187
	v_cndmask_b32_e64 v192, v209, v202, s[10:11]
	v_pk_mul_f32 v[172:173], v[172:173], v[190:191]
	v_cndmask_b32_e64 v191, v200, v208, s[12:13]
	v_add_f32_e32 v187, 1.0, v187
	v_rcp_f32_e32 v195, v187
	v_mov_b32_e32 v187, v97
	v_cndmask_b32_e64 v190, v198, v206, s[12:13]
	v_pk_mul_f32 v[192:193], v[128:129], v[192:193]
	v_mov_b32_dpp v187, v118 row_ror:1 row_mask:0xf bank_mask:0xf
	v_pk_mul_f32 v[188:189], v[188:189], v[194:195]
	v_cndmask_b32_e64 v195, v207, v199, s[10:11]
	v_cndmask_b32_e64 v194, v187, v197, s[10:11]
	v_pk_mul_f32 v[170:171], v[170:171], v[188:189]
	v_cndmask_b32_e64 v189, v205, v212, s[12:13]
	v_cndmask_b32_e64 v188, v203, v210, s[12:13]
	v_pk_mul_f32 v[194:195], v[126:127], v[194:195]
	v_pk_fma_f32 v[190:191], v[130:131], v[190:191], v[134:135]
	v_pk_fma_f32 v[188:189], v[132:133], v[188:189], v[136:137]
	v_pk_fma_f32 v[120:121], v[120:121], v[124:125], v[192:193]
	v_pk_fma_f32 v[118:119], v[118:119], v[122:123], v[194:195]
	v_pk_add_f32 v[120:121], v[120:121], v[188:189]
	v_pk_add_f32 v[118:119], v[118:119], v[190:191]
	v_mul_f32_e32 v190, 0xbfb8aa3b, v120
	v_mul_f32_e32 v188, 0xbfb8aa3b, v118
	v_mul_f32_e32 v189, 0xbfb8aa3b, v119
	v_mul_f32_e32 v191, 0xbfb8aa3b, v121
	v_exp_f32_e32 v188, v188
	v_exp_f32_e32 v189, v189
	v_exp_f32_e32 v190, v190
	v_exp_f32_e32 v191, v191
	v_add_f32_e32 v188, 1.0, v188
	v_add_f32_e32 v189, 1.0, v189
	v_add_f32_e32 v190, 1.0, v190
	v_add_f32_e32 v191, 1.0, v191
	v_rcp_f32_e32 v188, v188
	v_rcp_f32_e32 v189, v189
	v_rcp_f32_e32 v190, v190
	v_rcp_f32_e32 v191, v191
	v_mov_b32_e32 v192, v97
	v_mov_b32_e32 v194, v97
	v_mov_b32_e32 v193, v97
	v_mov_b32_dpp v192, v114 row_ror:1 row_mask:0xf bank_mask:0xf
	v_mov_b32_dpp v194, v115 row_ror:1 row_mask:0xf bank_mask:0xf
	v_mov_b32_e32 v195, v97
	v_mov_b32_e32 v197, v97
	v_mov_b32_e32 v199, v97
	v_pk_mul_f32 v[120:121], v[120:121], v[190:191]
	v_pk_mul_f32 v[118:119], v[118:119], v[188:189]
	v_mov_b32_dpp v193, v98 row_ror:15 row_mask:0xf bank_mask:0xf
	v_mov_b32_dpp v195, v99 row_ror:15 row_mask:0xf bank_mask:0xf
	v_mov_b32_dpp v197, v116 row_ror:1 row_mask:0xf bank_mask:0xf
	v_mov_b32_e32 v198, v97
	v_mov_b32_dpp v199, v117 row_ror:1 row_mask:0xf bank_mask:0xf
	v_mov_b32_e32 v200, v97
	v_cndmask_b32_e64 v191, v194, v207, s[10:11]
	v_cndmask_b32_e64 v190, v192, v187, s[10:11]
	v_pk_mul_f32 v[118:119], v[180:181], v[118:119]
	v_mov_b32_dpp v198, v100 row_ror:15 row_mask:0xf bank_mask:0xf
	v_mov_b32_dpp v200, v101 row_ror:15 row_mask:0xf bank_mask:0xf
	v_cndmask_b32_e64 v181, v208, v195, s[12:13]
	v_cndmask_b32_e64 v180, v206, v193, s[12:13]
	v_cndmask_b32_e64 v189, v199, v211, s[10:11]
	v_cndmask_b32_e64 v188, v197, v209, s[10:11]
	v_pk_mul_f32 v[190:191], v[126:127], v[190:191]
	v_pk_mul_f32 v[178:179], v[178:179], v[120:121]
	v_cndmask_b32_e64 v121, v212, v200, s[12:13]
	v_cndmask_b32_e64 v120, v210, v198, s[12:13]
	v_pk_fma_f32 v[180:181], v[130:131], v[180:181], v[134:135]
	v_pk_mul_f32 v[188:189], v[128:129], v[188:189]
	v_pk_fma_f32 v[114:115], v[114:115], v[122:123], v[190:191]
	v_pk_fma_f32 v[120:121], v[132:133], v[120:121], v[136:137]
	v_pk_fma_f32 v[116:117], v[116:117], v[124:125], v[188:189]
	v_pk_add_f32 v[114:115], v[114:115], v[180:181]
	v_pk_add_f32 v[116:117], v[116:117], v[120:121]
	v_mul_f32_e32 v120, 0xbfb8aa3b, v114
	v_mul_f32_e32 v121, 0xbfb8aa3b, v115
	v_exp_f32_e32 v120, v120
	v_exp_f32_e32 v121, v121
	v_mul_f32_e32 v180, 0xbfb8aa3b, v116
	v_mul_f32_e32 v181, 0xbfb8aa3b, v117
	v_exp_f32_e32 v180, v180
	v_exp_f32_e32 v181, v181
	v_add_f32_e32 v120, 1.0, v120
	v_add_f32_e32 v121, 1.0, v121
	v_rcp_f32_e32 v120, v120
	v_rcp_f32_e32 v121, v121
	v_add_f32_e32 v180, 1.0, v180
	v_add_f32_e32 v181, 1.0, v181
	v_rcp_f32_e32 v180, v180
	v_rcp_f32_e32 v181, v181
	v_pk_mul_f32 v[114:115], v[114:115], v[120:121]
	v_cndmask_b32_e64 v121, v200, 0, s[12:13]
	v_pk_mul_f32 v[114:115], v[176:177], v[114:115]
	v_pk_mul_f32 v[116:117], v[116:117], v[180:181]
	v_mov_b32_e32 v176, v97
	v_mov_b32_e32 v177, v97
	v_mov_b32_e32 v180, v97
	v_mov_b32_e32 v181, v97
	v_pk_mul_f32 v[174:175], v[174:175], v[116:117]
	v_mov_b32_dpp v176, v98 row_ror:1 row_mask:0xf bank_mask:0xf
	v_mov_b32_dpp v177, v99 row_ror:1 row_mask:0xf bank_mask:0xf
	v_mov_b32_dpp v180, v100 row_ror:1 row_mask:0xf bank_mask:0xf
	v_mov_b32_dpp v181, v101 row_ror:1 row_mask:0xf bank_mask:0xf
	v_cndmask_b32_e64 v117, v195, 0, s[12:13]
	v_cndmask_b32_e64 v116, v193, 0, s[12:13]
	v_cndmask_b32_e64 v120, v198, 0, s[12:13]
	v_pk_fma_f32 v[120:121], v[132:133], v[120:121], v[136:137]
	v_pk_fma_f32 v[116:117], v[130:131], v[116:117], v[134:135]
	v_cndmask_b32_e64 v131, v181, v199, s[10:11]
	v_cndmask_b32_e64 v130, v180, v197, s[10:11]
	v_cndmask_b32_e64 v133, v177, v194, s[10:11]
	v_cndmask_b32_e64 v132, v176, v192, s[10:11]
	v_pk_mul_f32 v[126:127], v[126:127], v[132:133]
	v_pk_mul_f32 v[128:129], v[128:129], v[130:131]
	v_pk_fma_f32 v[122:123], v[98:99], v[122:123], v[126:127]
	v_pk_fma_f32 v[124:125], v[100:101], v[124:125], v[128:129]
	v_pk_add_f32 v[116:117], v[116:117], v[122:123]
	v_pk_add_f32 v[120:121], v[120:121], v[124:125]
	v_mul_f32_e32 v122, 0xbfb8aa3b, v116
	v_mul_f32_e32 v123, 0xbfb8aa3b, v117
	v_mul_f32_e32 v124, 0xbfb8aa3b, v120
	v_mul_f32_e32 v125, 0xbfb8aa3b, v121
	v_exp_f32_e32 v122, v122
	v_exp_f32_e32 v123, v123
	v_exp_f32_e32 v124, v124
	v_exp_f32_e32 v125, v125
	v_add_f32_e32 v122, 1.0, v122
	v_add_f32_e32 v123, 1.0, v123
	v_add_f32_e32 v124, 1.0, v124
	v_add_f32_e32 v125, 1.0, v125
	v_rcp_f32_e32 v122, v122
	v_rcp_f32_e32 v123, v123
	v_rcp_f32_e32 v124, v124
	v_rcp_f32_e32 v125, v125
	v_pk_mul_f32 v[116:117], v[116:117], v[122:123]
	v_pk_mul_f32 v[120:121], v[120:121], v[124:125]
	s_nop 0
	v_pk_mul_f32 v[122:123], v[142:143], v[120:121]
	v_pk_mul_f32 v[124:125], v[144:145], v[116:117]
	v_cvt_pk_bf16_f32 v120, v172, v173
	v_cvt_pk_bf16_f32 v121, v170, v171
	v_cvt_pk_bf16_f32 v118, v118, v119
	v_cvt_pk_bf16_f32 v119, v178, v179
	v_cvt_pk_bf16_f32 v116, v114, v115
	v_cvt_pk_bf16_f32 v117, v174, v175
	s_nop 0
	v_cvt_pk_bf16_f32 v114, v124, v125
	v_cvt_pk_bf16_f32 v115, v122, v123
	s_and_saveexec_b64 s[22:23], s[8:9]
	s_cbranch_execz .LBB0_1048
;     __device__ __forceinline__ void operator()(const f32x4 (&acc)[2][2][4][2], const Unit& u, int wr, int wc, int fr_in, int fq_in) const {
;     ...
;                 const int ch = ch0 + 4 * n;
; #pragma unroll
;                 for (int pass = 0; pass < 2; ++pass) {
;                     const int co = pass ? DFF : 0;
;                     const f32x4 k0 = *(const f32x4*)(fk + co + ch), k1 = *(const f32x4*)(fk + DFF2 + co + ch), k2 = *(const f32x4*)(fk + 2 * DFF2 + co + ch), bb = *(const f32x4*)(fb + co + ch);
;                     f32x4 up_prev = (f32x4){0.f, 0.f, 0.f, 0.f}, up_cur, dn_cur, dn_next;
; #pragma unroll
;                     for (int j = 0; j < 4; ++j) dn_cur[j] = DPP_DN(acc[ai][pass][0][n][j]);
; #pragma unroll
;                     for (int m = 0; m < 4; ++m) {
;                         const f32x4 xv = acc[ai][pass][m][n];
; #pragma unroll
;                         for (int j = 0; j < 4; ++j) { up_cur[j] = DPP_UP(xv[j]); dn_next[j] = (m < 3) ? DPP_DN(acc[ai][pass][m < 3 ? m + 1 : 3][n][j]) : 0.f; }
;                         const f32x4 xp = f0 ? up_prev : up_cur, xn = f15 ? dn_next : dn_cur;
;                         const f32x4 c = (k0 * xp + k1 * xv) + (k2 * xn + bb);
;                         if (pass == 0) o[m] = c;
;                         else { f32x4 e;
; #pragma unroll
;                             for (int j = 0; j < 4; ++j) e[j] = __builtin_amdgcn_rcpf(1.0f + __builtin_amdgcn_exp2f(c[j] * -1.4426950408889634f));
;                             o[m] = o[m] * (c * e); }
;                         up_prev = up_cur; dn_cur = dn_next; }
;                 }
;                 if (n == 0) {
; #pragma unroll
;                     for (int m = 0; m < 4; ++m) { wlo[m].x = cvt_pk_bf16(o[m][0], o[m][1]); wlo[m].y = cvt_pk_bf16(o[m][2], o[m][3]); }
;                 } else {
; #pragma unroll
;                     for (int m = 0; m < 4; ++m) { u32x4 w; w.x = wlo[m].x; w.y = wlo[m].y; w.z = cvt_pk_bf16(o[m][0], o[m][1]); w.w = cvt_pk_bf16(o[m][2], o[m][3]);
;                         *(u32x4*)(base + off0 + (unsigned)(ai * HALF + m * 16) * (DFF * 2u)) = w; }
;                 }
;                 if (fr < 2 || fr >= 14) { const int k = fr < 2 ? fr : fr - 12;
;                     const f32x4 xv = fr < 2 ? acc[ai][0][0][n] : acc[ai][0][3][n], yv = fr < 2 ? acc[ai][1][0][n] : acc[ai][1][3][n];
	v_cndmask_b32_e64 v102, v98, v102, s[6:7]
	v_cndmask_b32_e64 v103, v99, v103, s[6:7]
	v_lshl_add_u64 v[98:99], v[158:159], 1, v[166:167]
	v_cndmask_b32_e64 v108, v108, v112, s[6:7]
	v_cndmask_b32_e64 v109, v109, v113, s[6:7]
	v_cndmask_b32_e64 v106, v106, v110, s[6:7]
	v_cndmask_b32_e64 v107, v107, v111, s[6:7]
	v_cndmask_b32_e64 v104, v100, v104, s[6:7]
	v_cndmask_b32_e64 v105, v101, v105, s[6:7]
	v_cvt_pk_bf16_f32 v100, v106, v107
	v_cvt_pk_bf16_f32 v101, v108, v109
	v_cvt_pk_bf16_f32 v102, v102, v103
	v_cvt_pk_bf16_f32 v103, v104, v105
	global_store_dwordx2 v[98:99], v[100:101], off
	v_add_co_u32_e32 v98, vcc, 0x1000, v98
	s_nop 1
	v_addc_co_u32_e32 v99, vcc, 0, v99, vcc
	global_store_dwordx2 v[98:99], v[102:103], off offset:1536
.LBB0_1048:
	s_or_b64 exec, exec, s[22:23]
	v_or_b32_e32 v126, 4, v158
	v_ashrrev_i32_e32 v127, 31, v126
	v_lshlrev_b64 v[98:99], 2, v[126:127]
	v_lshl_add_u64 v[130:131], s[90:91], 0, v[98:99]
	v_lshl_add_u64 v[128:129], s[92:93], 0, v[98:99]
	ds_read_b128 v[102:105], v213 offset:512
	ds_read_b128 v[98:101], v213 offset:576
	ds_read_b128 v[106:109], v213 offset:640
	ds_read_b128 v[110:113], v213 offset:704
	v_mov_b32_e32 v170, v97
	v_mov_b32_e32 v172, v97
	v_mov_b32_e32 v132, v97
	v_mov_b32_e32 v133, v97
	v_mov_b32_e32 v144, v97
	v_mov_b32_e32 v145, v97
	v_mov_b32_dpp v170, v78 row_ror:1 row_mask:0xf bank_mask:0xf
	v_mov_b32_e32 v171, v97
	v_mov_b32_dpp v172, v79 row_ror:1 row_mask:0xf bank_mask:0xf
	v_mov_b32_e32 v173, v97
	v_mov_b32_e32 v122, v97
	v_mov_b32_e32 v123, v97
	v_mov_b32_dpp v132, v78 row_ror:15 row_mask:0xf bank_mask:0xf
	v_mov_b32_dpp v133, v79 row_ror:15 row_mask:0xf bank_mask:0xf
	v_mov_b32_dpp v144, v76 row_ror:1 row_mask:0xf bank_mask:0xf
	v_mov_b32_e32 v142, v97
	v_mov_b32_dpp v145, v77 row_ror:1 row_mask:0xf bank_mask:0xf
	v_mov_b32_e32 v143, v97
	v_mov_b32_dpp v171, v94 row_ror:15 row_mask:0xf bank_mask:0xf
	v_mov_b32_dpp v173, v95 row_ror:15 row_mask:0xf bank_mask:0xf
	v_cndmask_b32_e64 v135, v172, 0, s[10:11]
	v_cndmask_b32_e64 v134, v170, 0, s[10:11]
	v_mov_b32_dpp v122, v76 row_ror:15 row_mask:0xf bank_mask:0xf
	v_mov_b32_dpp v123, v77 row_ror:15 row_mask:0xf bank_mask:0xf
	v_mov_b32_dpp v142, v92 row_ror:15 row_mask:0xf bank_mask:0xf
	v_mov_b32_dpp v143, v93 row_ror:15 row_mask:0xf bank_mask:0xf
	v_cndmask_b32_e64 v133, v133, v173, s[12:13]
	v_cndmask_b32_e64 v132, v132, v171, s[12:13]
	v_cndmask_b32_e64 v137, v145, 0, s[10:11]
	v_cndmask_b32_e64 v136, v144, 0, s[10:11]
	v_mov_b32_e32 v175, v97
	v_mov_b32_e32 v177, v97
	v_mov_b32_e32 v178, v97
	v_mov_b32_e32 v180, v97
	v_cndmask_b32_e64 v123, v123, v143, s[12:13]
	v_cndmask_b32_e64 v122, v122, v142, s[12:13]
	v_mov_b32_e32 v174, v97
	v_mov_b32_dpp v175, v88 row_ror:15 row_mask:0xf bank_mask:0xf
	v_mov_b32_e32 v176, v97
	v_mov_b32_dpp v177, v89 row_ror:15 row_mask:0xf bank_mask:0xf
	v_mov_b32_dpp v178, v94 row_ror:1 row_mask:0xf bank_mask:0xf
	v_mov_b32_e32 v179, v97
	v_mov_b32_dpp v180, v95 row_ror:1 row_mask:0xf bank_mask:0xf
	v_mov_b32_e32 v181, v97
	v_mov_b32_dpp v174, v92 row_ror:1 row_mask:0xf bank_mask:0xf
	v_mov_b32_dpp v176, v93 row_ror:1 row_mask:0xf bank_mask:0xf
	v_mov_b32_dpp v179, v90 row_ror:15 row_mask:0xf bank_mask:0xf
	v_mov_b32_dpp v181, v91 row_ror:15 row_mask:0xf bank_mask:0xf
	v_cndmask_b32_e64 v145, v176, v145, s[10:11]
	v_cndmask_b32_e64 v144, v174, v144, s[10:11]
	v_mov_b32_e32 v187, v97
	v_mov_b32_e32 v189, v97
	v_mov_b32_e32 v188, v97
	v_mov_b32_dpp v187, v90 row_ror:1 row_mask:0xf bank_mask:0xf
	v_mov_b32_dpp v189, v91 row_ror:1 row_mask:0xf bank_mask:0xf
	v_mov_b32_e32 v190, v97
	v_mov_b32_dpp v188, v74 row_ror:15 row_mask:0xf bank_mask:0xf
	s_lshl_b32 s0, s42, 8
	v_mov_b32_dpp v190, v75 row_ror:15 row_mask:0xf bank_mask:0xf
	s_mul_i32 s1, s42, 0x160000
	v_readlane_b32 s22, v254, 37
	s_mul_hi_i32 s0, s0, 0x1600
	v_readlane_b32 s23, v254, 38
	s_add_u32 s42, s22, s1
	s_addc_u32 s43, s23, s0
	v_add_u32_e32 v96, s49, v96
	s_movk_i32 s0, 0x1600
	v_mul_lo_u32 v96, v96, s0
	v_lshl_add_u32 v96, v158, 1, v96
	v_lshl_add_u64 v[124:125], s[42:43], 0, v[96:97]
	s_mov_b32 s0, 0x16000
	s_waitcnt lgkmcnt(3)
	v_pk_mul_f32 v[134:135], v[104:105], v[134:135]
	v_pk_mul_f32 v[136:137], v[102:103], v[136:137]
	s_waitcnt lgkmcnt(2)
	v_pk_fma_f32 v[134:135], v[78:79], v[100:101], v[134:135]
	s_waitcnt lgkmcnt(0)
; #define DPP_UP(v) __int_as_float(__builtin_amdgcn_update_dpp(0, __float_as_int(v), 0x121, 0xf, 0xf, false))
; #define DPP_DN(v) __int_as_float(__builtin_amdgcn_update_dpp(0, __float_as_int(v), 0x12F, 0xf, 0xf, false))
;     __device__ __forceinline__ void operator()(const f32x4 (&acc)[2][2][4][2], const Unit& u, int wr, int wc, int fr_in, int fq_in) const {
;     ...
;                     const f32x4 k0 = *(const f32x4*)(fk + co + ch), k1 = *(const f32x4*)(fk + DFF2 + co + ch), k2 = *(const f32x4*)(fk + 2 * DFF2 + co + ch), bb = *(const f32x4*)(fb + co + ch);
;                     f32x4 up_prev = (f32x4){0.f, 0.f, 0.f, 0.f}, up_cur, dn_cur, dn_next;
; #pragma unroll
;                     for (int j = 0; j < 4; ++j) dn_cur[j] = DPP_DN(acc[ai][pass][0][n][j]);
; #pragma unroll
;                     for (int m = 0; m < 4; ++m) {
;                         const f32x4 xv = acc[ai][pass][m][n];
; #pragma unroll
;                         for (int j = 0; j < 4; ++j) { up_cur[j] = DPP_UP(xv[j]); dn_next[j] = (m < 3) ? DPP_DN(acc[ai][pass][m < 3 ? m + 1 : 3][n][j]) : 0.f; }
;                         const f32x4 xp = f0 ? up_prev : up_cur, xn = f15 ? dn_next : dn_cur;
;                         const f32x4 c = (k0 * xp + k1 * xv) + (k2 * xn + bb);
;                         if (pass == 0) o[m] = c;
;                         else { f32x4 e;
; #pragma unroll
;                             for (int j = 0; j < 4; ++j) e[j] = __builtin_amdgcn_rcpf(1.0f + __builtin_amdgcn_exp2f(c[j] * -1.4426950408889634f));
;                             o[m] = o[m] * (c * e); }
;                         up_prev = up_cur; dn_cur = dn_next; }
	v_pk_fma_f32 v[132:133], v[108:109], v[132:133], v[112:113]
	v_pk_fma_f32 v[122:123], v[106:107], v[122:123], v[110:111]
	v_pk_fma_f32 v[136:137], v[76:77], v[98:99], v[136:137]
	v_pk_add_f32 v[132:133], v[134:135], v[132:133]
	v_cndmask_b32_e64 v135, v143, v177, s[12:13]
	v_cndmask_b32_e64 v134, v142, v175, s[12:13]
	v_cndmask_b32_e64 v143, v180, v172, s[10:11]
	v_cndmask_b32_e64 v142, v178, v170, s[10:11]
	v_pk_add_f32 v[122:123], v[136:137], v[122:123]
	v_cndmask_b32_e64 v137, v173, v181, s[12:13]
	v_cndmask_b32_e64 v136, v171, v179, s[12:13]
	v_pk_mul_f32 v[142:143], v[104:105], v[142:143]
	v_mov_b32_e32 v170, v97
	v_mov_b32_e32 v172, v97
	v_pk_fma_f32 v[136:137], v[108:109], v[136:137], v[112:113]
	v_pk_mul_f32 v[144:145], v[102:103], v[144:145]
	v_pk_fma_f32 v[94:95], v[94:95], v[100:101], v[142:143]
	v_mov_b32_dpp v170, v88 row_ror:1 row_mask:0xf bank_mask:0xf
	v_mov_b32_e32 v171, v97
	v_mov_b32_dpp v172, v89 row_ror:1 row_mask:0xf bank_mask:0xf
	v_mov_b32_e32 v173, v97
	v_pk_fma_f32 v[134:135], v[106:107], v[134:135], v[110:111]
	v_pk_fma_f32 v[92:93], v[92:93], v[98:99], v[144:145]
	v_pk_add_f32 v[142:143], v[94:95], v[136:137]
	v_mov_b32_dpp v171, v72 row_ror:15 row_mask:0xf bank_mask:0xf
	v_mov_b32_dpp v173, v73 row_ror:15 row_mask:0xf bank_mask:0xf
	v_cndmask_b32_e64 v137, v172, v176, s[10:11]
	v_cndmask_b32_e64 v136, v170, v174, s[10:11]
	v_pk_add_f32 v[144:145], v[92:93], v[134:135]
	v_cndmask_b32_e64 v93, v177, v173, s[12:13]
	v_cndmask_b32_e64 v92, v175, v171, s[12:13]
	v_pk_mul_f32 v[136:137], v[102:103], v[136:137]
	v_pk_fma_f32 v[92:93], v[106:107], v[92:93], v[110:111]
	v_pk_fma_f32 v[88:89], v[88:89], v[98:99], v[136:137]
	v_cndmask_b32_e64 v135, v189, v180, s[10:11]
	v_cndmask_b32_e64 v134, v187, v178, s[10:11]
	v_pk_add_f32 v[136:137], v[88:89], v[92:93]
	v_mov_b32_e32 v92, v97
	v_mov_b32_e32 v93, v97
	v_cndmask_b32_e64 v95, v181, v190, s[12:13]
	v_cndmask_b32_e64 v94, v179, v188, s[12:13]
	v_pk_mul_f32 v[134:135], v[104:105], v[134:135]
	v_mov_b32_dpp v92, v74 row_ror:1 row_mask:0xf bank_mask:0xf
	v_mov_b32_dpp v93, v75 row_ror:1 row_mask:0xf bank_mask:0xf
	v_pk_fma_f32 v[94:95], v[108:109], v[94:95], v[112:113]
	v_pk_fma_f32 v[90:91], v[90:91], v[100:101], v[134:135]
	v_cndmask_b32_e64 v93, v93, v189, s[10:11]
	v_cndmask_b32_e64 v92, v92, v187, s[10:11]
	v_pk_add_f32 v[134:135], v[90:91], v[94:95]
	v_mov_b32_e32 v94, v97
	v_mov_b32_e32 v95, v97
	v_cndmask_b32_e64 v91, v190, 0, s[12:13]
	v_cndmask_b32_e64 v90, v188, 0, s[12:13]
	v_pk_mul_f32 v[92:93], v[104:105], v[92:93]
	v_mov_b32_dpp v94, v72 row_ror:1 row_mask:0xf bank_mask:0xf
	v_mov_b32_dpp v95, v73 row_ror:1 row_mask:0xf bank_mask:0xf
	v_pk_fma_f32 v[90:91], v[108:109], v[90:91], v[112:113]
	v_pk_fma_f32 v[92:93], v[74:75], v[100:101], v[92:93]
	v_cndmask_b32_e64 v95, v95, v172, s[10:11]
	v_cndmask_b32_e64 v94, v94, v170, s[10:11]
	v_pk_add_f32 v[108:109], v[90:91], v[92:93]
	v_add_co_u32_e32 v92, vcc, s82, v130
	v_cndmask_b32_e64 v89, v173, 0, s[12:13]
	v_cndmask_b32_e64 v88, v171, 0, s[12:13]
	v_pk_mul_f32 v[94:95], v[102:103], v[94:95]
	v_addc_co_u32_e32 v93, vcc, 0, v131, vcc
	v_pk_fma_f32 v[88:89], v[106:107], v[88:89], v[110:111]
	v_pk_fma_f32 v[94:95], v[72:73], v[98:99], v[94:95]
	v_add_co_u32_e32 v98, vcc, s82, v128
	v_pk_add_f32 v[106:107], v[88:89], v[94:95]
	ds_read_b128 v[88:91], v213 offset:768
	v_addc_co_u32_e32 v99, vcc, 0, v129, vcc
	ds_read_b128 v[92:95], v213 offset:832
	s_nop 0
	ds_read_b128 v[98:101], v213 offset:896
	s_nop 0
	ds_read_b128 v[102:105], v213 offset:960
	v_mov_b32_e32 v170, v97
	v_mov_b32_e32 v172, v97
	v_mov_b32_e32 v174, v97
	v_mov_b32_e32 v176, v97
	v_mov_b32_e32 v112, v97
	v_mov_b32_e32 v113, v97
	v_mov_b32_e32 v110, v97
	v_mov_b32_e32 v111, v97
	v_mov_b32_dpp v170, v64 row_ror:1 row_mask:0xf bank_mask:0xf
	v_mov_b32_e32 v171, v97
	v_mov_b32_dpp v172, v65 row_ror:1 row_mask:0xf bank_mask:0xf
	v_mov_b32_e32 v173, v97
	v_mov_b32_dpp v174, v66 row_ror:1 row_mask:0xf bank_mask:0xf
	v_mov_b32_e32 v175, v97
	v_mov_b32_dpp v176, v67 row_ror:1 row_mask:0xf bank_mask:0xf
	v_mov_b32_e32 v177, v97
	v_mov_b32_dpp v112, v64 row_ror:15 row_mask:0xf bank_mask:0xf
	v_mov_b32_dpp v113, v65 row_ror:15 row_mask:0xf bank_mask:0xf
	v_mov_b32_dpp v110, v66 row_ror:15 row_mask:0xf bank_mask:0xf
	v_mov_b32_dpp v111, v67 row_ror:15 row_mask:0xf bank_mask:0xf
	v_mov_b32_dpp v171, v84 row_ror:15 row_mask:0xf bank_mask:0xf
	v_mov_b32_dpp v173, v85 row_ror:15 row_mask:0xf bank_mask:0xf
	v_mov_b32_dpp v175, v86 row_ror:15 row_mask:0xf bank_mask:0xf
	v_mov_b32_dpp v177, v87 row_ror:15 row_mask:0xf bank_mask:0xf
	v_cndmask_b32_e64 v139, v172, 0, s[10:11]
	v_cndmask_b32_e64 v138, v170, 0, s[10:11]
	v_cndmask_b32_e64 v141, v176, 0, s[10:11]
	v_cndmask_b32_e64 v140, v174, 0, s[10:11]
	v_cndmask_b32_e64 v111, v111, v177, s[12:13]
	v_cndmask_b32_e64 v110, v110, v175, s[12:13]
	v_cndmask_b32_e64 v113, v113, v173, s[12:13]
	v_cndmask_b32_e64 v112, v112, v171, s[12:13]
	v_mov_b32_e32 v178, v97
	v_mov_b32_e32 v180, v97
	v_mov_b32_e32 v187, v97
	v_mov_b32_e32 v189, v97
	v_mov_b32_dpp v178, v84 row_ror:1 row_mask:0xf bank_mask:0xf
	v_mov_b32_e32 v179, v97
	v_mov_b32_dpp v180, v85 row_ror:1 row_mask:0xf bank_mask:0xf
	v_mov_b32_e32 v181, v97
	v_mov_b32_dpp v187, v86 row_ror:1 row_mask:0xf bank_mask:0xf
	v_mov_b32_e32 v188, v97
	v_mov_b32_dpp v189, v87 row_ror:1 row_mask:0xf bank_mask:0xf
	v_mov_b32_e32 v190, v97
	v_mov_b32_dpp v179, v80 row_ror:15 row_mask:0xf bank_mask:0xf
	v_mov_b32_dpp v181, v81 row_ror:15 row_mask:0xf bank_mask:0xf
	v_mov_b32_dpp v188, v82 row_ror:15 row_mask:0xf bank_mask:0xf
	v_mov_b32_dpp v190, v83 row_ror:15 row_mask:0xf bank_mask:0xf
	s_waitcnt lgkmcnt(3)
; __device__ __forceinline__ unsigned cvt_pk_bf16(float lo, float hi) { unsigned r; asm volatile("v_cvt_pk_bf16_f32 %0, %1, %2" : "=v"(r) : "v"(lo), "v"(hi)); return r; }
; #define DPP_UP(v) __int_as_float(__builtin_amdgcn_update_dpp(0, __float_as_int(v), 0x121, 0xf, 0xf, false))
; #define DPP_DN(v) __int_as_float(__builtin_amdgcn_update_dpp(0, __float_as_int(v), 0x12F, 0xf, 0xf, false))
;     __device__ __forceinline__ void operator()(const f32x4 (&acc)[2][2][4][2], const Unit& u, int wr, int wc, int fr_in, int fq_in) const {
;     ...
;                     const f32x4 k0 = *(const f32x4*)(fk + co + ch), k1 = *(const f32x4*)(fk + DFF2 + co + ch), k2 = *(const f32x4*)(fk + 2 * DFF2 + co + ch), bb = *(const f32x4*)(fb + co + ch);
;                     f32x4 up_prev = (f32x4){0.f, 0.f, 0.f, 0.f}, up_cur, dn_cur, dn_next;
; #pragma unroll
;                     for (int j = 0; j < 4; ++j) dn_cur[j] = DPP_DN(acc[ai][pass][0][n][j]);
; #pragma unroll
;                     for (int m = 0; m < 4; ++m) {
;                         const f32x4 xv = acc[ai][pass][m][n];
; #pragma unroll
;                         for (int j = 0; j < 4; ++j) { up_cur[j] = DPP_UP(xv[j]); dn_next[j] = (m < 3) ? DPP_DN(acc[ai][pass][m < 3 ? m + 1 : 3][n][j]) : 0.f; }
;                         const f32x4 xp = f0 ? up_prev : up_cur, xn = f15 ? dn_next : dn_cur;
;                         const f32x4 c = (k0 * xp + k1 * xv) + (k2 * xn + bb);
;                         if (pass == 0) o[m] = c;
;                         else { f32x4 e;
; #pragma unroll
;                             for (int j = 0; j < 4; ++j) e[j] = __builtin_amdgcn_rcpf(1.0f + __builtin_amdgcn_exp2f(c[j] * -1.4426950408889634f));
;                             o[m] = o[m] * (c * e); }
;                         up_prev = up_cur; dn_cur = dn_next; }
;                 }
;                 if (n == 0) {
; #pragma unroll
;                     for (int m = 0; m < 4; ++m) { wlo[m].x = cvt_pk_bf16(o[m][0], o[m][1]); wlo[m].y = cvt_pk_bf16(o[m][2], o[m][3]); }
	v_pk_mul_f32 v[140:141], v[90:91], v[140:141]
	v_pk_mul_f32 v[138:139], v[88:89], v[138:139]
	s_waitcnt lgkmcnt(2)
	v_pk_fma_f32 v[140:141], v[66:67], v[94:95], v[140:141]
	s_waitcnt lgkmcnt(0)
	v_pk_fma_f32 v[112:113], v[98:99], v[112:113], v[102:103]
	v_pk_fma_f32 v[110:111], v[100:101], v[110:111], v[104:105]
	v_pk_fma_f32 v[138:139], v[64:65], v[92:93], v[138:139]
	v_pk_add_f32 v[110:111], v[140:141], v[110:111]
	v_pk_add_f32 v[112:113], v[138:139], v[112:113]
	v_mul_f32_e32 v140, 0xbfb8aa3b, v110
	v_mul_f32_e32 v138, 0xbfb8aa3b, v112
	v_mul_f32_e32 v139, 0xbfb8aa3b, v113
	v_mul_f32_e32 v141, 0xbfb8aa3b, v111
	v_exp_f32_e32 v138, v138
	v_exp_f32_e32 v139, v139
	v_exp_f32_e32 v140, v140
	v_exp_f32_e32 v141, v141
	v_add_f32_e32 v138, 1.0, v138
	v_add_f32_e32 v139, 1.0, v139
	v_add_f32_e32 v140, 1.0, v140
	v_add_f32_e32 v141, 1.0, v141
	v_rcp_f32_e32 v138, v138
	v_rcp_f32_e32 v139, v139
	v_rcp_f32_e32 v140, v140
	v_rcp_f32_e32 v141, v141
	v_pk_mul_f32 v[112:113], v[112:113], v[138:139]
	v_cndmask_b32_e64 v139, v180, v172, s[10:11]
	v_pk_mul_f32 v[110:111], v[110:111], v[140:141]
	v_cndmask_b32_e64 v138, v178, v170, s[10:11]
	v_cndmask_b32_e64 v141, v189, v176, s[10:11]
	v_cndmask_b32_e64 v140, v187, v174, s[10:11]
	v_pk_mul_f32 v[110:111], v[132:133], v[110:111]
	v_pk_mul_f32 v[112:113], v[122:123], v[112:113]
	v_cndmask_b32_e64 v123, v177, v190, s[12:13]
	v_cndmask_b32_e64 v122, v175, v188, s[12:13]
	v_cndmask_b32_e64 v133, v173, v181, s[12:13]
	v_cndmask_b32_e64 v132, v171, v179, s[12:13]
	v_pk_mul_f32 v[140:141], v[90:91], v[140:141]
	v_pk_mul_f32 v[138:139], v[88:89], v[138:139]
	v_pk_fma_f32 v[132:133], v[98:99], v[132:133], v[102:103]
	v_pk_fma_f32 v[122:123], v[100:101], v[122:123], v[104:105]
	v_pk_fma_f32 v[86:87], v[86:87], v[94:95], v[140:141]
	v_pk_fma_f32 v[84:85], v[84:85], v[92:93], v[138:139]
	v_pk_add_f32 v[86:87], v[86:87], v[122:123]
	v_pk_add_f32 v[84:85], v[84:85], v[132:133]
	v_mul_f32_e32 v132, 0xbfb8aa3b, v86
	v_mul_f32_e32 v122, 0xbfb8aa3b, v84
	v_mul_f32_e32 v123, 0xbfb8aa3b, v85
	v_mul_f32_e32 v133, 0xbfb8aa3b, v87
	v_exp_f32_e32 v122, v122
	v_exp_f32_e32 v123, v123
	v_exp_f32_e32 v132, v132
	v_exp_f32_e32 v133, v133
	v_add_f32_e32 v122, 1.0, v122
	v_add_f32_e32 v123, 1.0, v123
	v_add_f32_e32 v132, 1.0, v132
	v_add_f32_e32 v133, 1.0, v133
	v_rcp_f32_e32 v122, v122
	v_rcp_f32_e32 v123, v123
	v_rcp_f32_e32 v132, v132
	v_rcp_f32_e32 v133, v133
	v_mov_b32_e32 v170, v97
	v_pk_mul_f32 v[122:123], v[84:85], v[122:123]
	v_mov_b32_e32 v172, v97
	v_pk_mul_f32 v[84:85], v[86:87], v[132:133]
	v_pk_mul_f32 v[86:87], v[144:145], v[122:123]
	v_pk_mul_f32 v[84:85], v[142:143], v[84:85]
	v_mov_b32_e32 v142, v97
	v_mov_b32_e32 v144, v97
	v_mov_b32_e32 v143, v97
	v_mov_b32_dpp v142, v80 row_ror:1 row_mask:0xf bank_mask:0xf
	v_mov_b32_dpp v144, v81 row_ror:1 row_mask:0xf bank_mask:0xf
	v_mov_b32_e32 v145, v97
	v_mov_b32_dpp v170, v82 row_ror:1 row_mask:0xf bank_mask:0xf
	v_mov_b32_e32 v171, v97
	v_mov_b32_dpp v172, v83 row_ror:1 row_mask:0xf bank_mask:0xf
	v_mov_b32_e32 v173, v97
	v_mov_b32_dpp v143, v68 row_ror:15 row_mask:0xf bank_mask:0xf
	v_mov_b32_dpp v145, v69 row_ror:15 row_mask:0xf bank_mask:0xf
	v_mov_b32_dpp v171, v70 row_ror:15 row_mask:0xf bank_mask:0xf
	v_mov_b32_dpp v173, v71 row_ror:15 row_mask:0xf bank_mask:0xf
	v_cndmask_b32_e64 v139, v144, v180, s[10:11]
	v_cndmask_b32_e64 v138, v142, v178, s[10:11]
	v_cndmask_b32_e64 v141, v172, v189, s[10:11]
	v_cndmask_b32_e64 v140, v170, v187, s[10:11]
	v_cndmask_b32_e64 v123, v190, v173, s[12:13]
	v_cndmask_b32_e64 v122, v188, v171, s[12:13]
	v_cndmask_b32_e64 v133, v181, v145, s[12:13]
	v_cndmask_b32_e64 v132, v179, v143, s[12:13]
	v_pk_mul_f32 v[140:141], v[90:91], v[140:141]
	v_pk_mul_f32 v[138:139], v[88:89], v[138:139]
	v_pk_fma_f32 v[132:133], v[98:99], v[132:133], v[102:103]
	v_pk_fma_f32 v[122:123], v[100:101], v[122:123], v[104:105]
	v_pk_fma_f32 v[82:83], v[82:83], v[94:95], v[140:141]
	v_pk_fma_f32 v[80:81], v[80:81], v[92:93], v[138:139]
	v_pk_add_f32 v[82:83], v[82:83], v[122:123]
	v_pk_add_f32 v[80:81], v[80:81], v[132:133]
	v_mul_f32_e32 v132, 0xbfb8aa3b, v82
	v_mul_f32_e32 v122, 0xbfb8aa3b, v80
	v_mul_f32_e32 v123, 0xbfb8aa3b, v81
	v_mul_f32_e32 v133, 0xbfb8aa3b, v83
	v_exp_f32_e32 v122, v122
	v_exp_f32_e32 v123, v123
	v_exp_f32_e32 v132, v132
	v_exp_f32_e32 v133, v133
	v_add_f32_e32 v122, 1.0, v122
	v_add_f32_e32 v123, 1.0, v123
	v_add_f32_e32 v132, 1.0, v132
	v_add_f32_e32 v133, 1.0, v133
	v_rcp_f32_e32 v122, v122
	v_rcp_f32_e32 v123, v123
	v_rcp_f32_e32 v132, v132
	v_rcp_f32_e32 v133, v133
	v_pk_mul_f32 v[80:81], v[80:81], v[122:123]
	s_nop 0
	v_pk_mul_f32 v[80:81], v[136:137], v[80:81]
	v_pk_mul_f32 v[82:83], v[82:83], v[132:133]
	v_mov_b32_e32 v136, v97
	v_pk_mul_f32 v[82:83], v[134:135], v[82:83]
	v_mov_b32_e32 v134, v97
	v_mov_b32_e32 v135, v97
	v_mov_b32_e32 v137, v97
	v_mov_b32_dpp v134, v68 row_ror:1 row_mask:0xf bank_mask:0xf
	v_mov_b32_dpp v135, v69 row_ror:1 row_mask:0xf bank_mask:0xf
	v_mov_b32_dpp v136, v70 row_ror:1 row_mask:0xf bank_mask:0xf
	v_mov_b32_dpp v137, v71 row_ror:1 row_mask:0xf bank_mask:0xf
	v_cndmask_b32_e64 v123, v145, 0, s[12:13]
	v_cndmask_b32_e64 v122, v143, 0, s[12:13]
	v_cndmask_b32_e64 v133, v173, 0, s[12:13]
	v_cndmask_b32_e64 v132, v171, 0, s[12:13]
	v_pk_fma_f32 v[100:101], v[100:101], v[132:133], v[104:105]
	v_pk_fma_f32 v[98:99], v[98:99], v[122:123], v[102:103]
	v_cndmask_b32_e64 v103, v135, v144, s[10:11]
	v_cndmask_b32_e64 v102, v134, v142, s[10:11]
	v_cndmask_b32_e64 v105, v137, v172, s[10:11]
	v_cndmask_b32_e64 v104, v136, v170, s[10:11]
	v_pk_mul_f32 v[90:91], v[90:91], v[104:105]
	v_pk_mul_f32 v[88:89], v[88:89], v[102:103]
;     __device__ __forceinline__ void operator()(const f32x4 (&acc)[2][2][4][2], const Unit& u, int wr, int wc, int fr_in, int fq_in) const {
;     ...
;         for (int ai = 0; ai < 2; ++ai) {
;             f32x4 o[4]; u32x2 wlo[4];
; #pragma unroll
;             for (int n = 0; n < 2; ++n) {
;                 const int ch = ch0 + 4 * n;
; #pragma unroll
;                 for (int pass = 0; pass < 2; ++pass) {
;                     const int co = pass ? DFF : 0;
;                     const f32x4 k0 = *(const f32x4*)(fk + co + ch), k1 = *(const f32x4*)(fk + DFF2 + co + ch), k2 = *(const f32x4*)(fk + 2 * DFF2 + co + ch), bb = *(const f32x4*)(fb + co + ch);
;                     f32x4 up_prev = (f32x4){0.f, 0.f, 0.f, 0.f}, up_cur, dn_cur, dn_next;
; #pragma unroll
;                     for (int j = 0; j < 4; ++j) dn_cur[j] = DPP_DN(acc[ai][pass][0][n][j]);
; #pragma unroll
;                     for (int m = 0; m < 4; ++m) {
;                         const f32x4 xv = acc[ai][pass][m][n];
; #pragma unroll
;                         for (int j = 0; j < 4; ++j) { up_cur[j] = DPP_UP(xv[j]); dn_next[j] = (m < 3) ? DPP_DN(acc[ai][pass][m < 3 ? m + 1 : 3][n][j]) : 0.f; }
;                         const f32x4 xp = f0 ? up_prev : up_cur, xn = f15 ? dn_next : dn_cur;
;                         const f32x4 c = (k0 * xp + k1 * xv) + (k2 * xn + bb);
;                         if (pass == 0) o[m] = c;
;                         else { f32x4 e;
; #pragma unroll
;                             for (int j = 0; j < 4; ++j) e[j] = __builtin_amdgcn_rcpf(1.0f + __builtin_amdgcn_exp2f(c[j] * -1.4426950408889634f));
;                             o[m] = o[m] * (c * e); }
;                         up_prev = up_cur; dn_cur = dn_next; }
;                 }
;                 if (n == 0) {
; #pragma unroll
;                     for (int m = 0; m < 4; ++m) { wlo[m].x = cvt_pk_bf16(o[m][0], o[m][1]); wlo[m].y = cvt_pk_bf16(o[m][2], o[m][3]); }
;                 } else {
; #pragma unroll
;                     for (int m = 0; m < 4; ++m) { u32x4 w; w.x = wlo[m].x; w.y = wlo[m].y; w.z = cvt_pk_bf16(o[m][0], o[m][1]); w.w = cvt_pk_bf16(o[m][2], o[m][3]);
;                         *(u32x4*)(base + off0 + (unsigned)(ai * HALF + m * 16) * (DFF * 2u)) = w; }
;                 }
;                 if (fr < 2 || fr >= 14) { const int k = fr < 2 ? fr : fr - 12;
	v_pk_fma_f32 v[90:91], v[70:71], v[94:95], v[90:91]
	v_pk_fma_f32 v[88:89], v[68:69], v[92:93], v[88:89]
	v_pk_add_f32 v[90:91], v[100:101], v[90:91]
	v_pk_add_f32 v[88:89], v[98:99], v[88:89]
	v_mul_f32_e32 v94, 0xbfb8aa3b, v90
	v_mul_f32_e32 v92, 0xbfb8aa3b, v88
	v_mul_f32_e32 v93, 0xbfb8aa3b, v89
	v_mul_f32_e32 v95, 0xbfb8aa3b, v91
	v_exp_f32_e32 v92, v92
	v_exp_f32_e32 v93, v93
	v_exp_f32_e32 v94, v94
	v_exp_f32_e32 v95, v95
	v_add_f32_e32 v92, 1.0, v92
	v_add_f32_e32 v93, 1.0, v93
	v_add_f32_e32 v94, 1.0, v94
	v_add_f32_e32 v95, 1.0, v95
	v_cvt_pk_bf16_f32 v122, v112, v113
	v_cvt_pk_bf16_f32 v123, v110, v111
	global_store_dwordx4 v96, v[120:123], s[42:43]
	v_rcp_f32_e32 v92, v92
	v_rcp_f32_e32 v93, v93
	v_cvt_pk_bf16_f32 v120, v86, v87
	v_cvt_pk_bf16_f32 v121, v84, v85
	v_add_co_u32_e32 v84, vcc, s0, v124
	v_rcp_f32_e32 v94, v94
	v_rcp_f32_e32 v95, v95
	v_addc_co_u32_e32 v85, vcc, 0, v125, vcc
	s_mov_b32 s0, 0x2c000
	global_store_dwordx4 v[84:85], v[118:121], off
	v_pk_mul_f32 v[90:91], v[90:91], v[94:95]
	v_pk_mul_f32 v[88:89], v[88:89], v[92:93]
	v_cvt_pk_bf16_f32 v118, v80, v81
	v_add_co_u32_e32 v80, vcc, s0, v124
	v_cvt_pk_bf16_f32 v119, v82, v83
	v_pk_mul_f32 v[90:91], v[108:109], v[90:91]
	s_nop 0
	v_addc_co_u32_e32 v81, vcc, 0, v125, vcc
	global_store_dwordx4 v[80:81], v[116:119], off
	v_add_co_u32_e32 v80, vcc, 0x42000, v124
	v_pk_mul_f32 v[88:89], v[106:107], v[88:89]
	s_nop 0
	v_addc_co_u32_e32 v81, vcc, 0, v125, vcc
	v_cvt_pk_bf16_f32 v116, v88, v89
	v_cvt_pk_bf16_f32 v117, v90, v91
	global_store_dwordx4 v[80:81], v[114:117], off
	s_and_saveexec_b64 s[22:23], s[8:9]
	s_cbranch_execz .LBB0_1050
	v_cndmask_b32_e64 v68, v68, v64, s[6:7]
	v_cndmask_b32_e64 v69, v69, v65, s[6:7]
	v_lshl_add_u64 v[64:65], v[126:127], 1, v[166:167]
	v_cndmask_b32_e64 v74, v74, v78, s[6:7]
	v_cndmask_b32_e64 v75, v75, v79, s[6:7]
	v_cndmask_b32_e64 v72, v72, v76, s[6:7]
	v_cndmask_b32_e64 v73, v73, v77, s[6:7]
	v_cndmask_b32_e64 v70, v70, v66, s[6:7]
	v_cndmask_b32_e64 v71, v71, v67, s[6:7]
	v_cvt_pk_bf16_f32 v66, v72, v73
	v_cvt_pk_bf16_f32 v67, v74, v75
	v_cvt_pk_bf16_f32 v68, v68, v69
	v_cvt_pk_bf16_f32 v69, v70, v71
	global_store_dwordx2 v[64:65], v[66:67], off
	v_add_co_u32_e32 v64, vcc, 0x1000, v64
	s_nop 1
	v_addc_co_u32_e32 v65, vcc, 0, v65, vcc
	global_store_dwordx2 v[64:65], v[68:69], off offset:1536
.LBB0_1050:
	s_or_b64 exec, exec, s[22:23]
	s_mov_b64 s[0:1], 0x2c00
	v_add_u32_e32 v66, 8, v186
	v_mov_b64_e32 v[64:65], s[40:41]
	v_lshl_add_u64 v[100:101], v[160:161], 0, s[0:1]
	v_lshl_add_u64 v[102:103], v[168:169], 0, s[0:1]
	v_lshl_add_u64 v[90:91], v[164:165], 0, s[0:1]
	v_lshl_add_u64 v[92:93], v[162:163], 0, s[0:1]
	v_mad_i64_i32 v[80:81], s[0:1], v66, s45, v[64:65]
	ds_read_b128 v[68:71], v213 offset:0
	ds_read_b128 v[64:67], v213 offset:64
	ds_read_b128 v[72:75], v213 offset:128
	ds_read_b128 v[76:79], v213 offset:192
	v_mov_b32_e32 v99, v97
	v_mov_b32_e32 v105, v97
	v_mov_b32_e32 v84, v97
	v_mov_b32_e32 v85, v97
	v_mov_b32_e32 v96, v97
	v_mov_b32_e32 v98, v97
	v_mov_b32_dpp v99, v46 row_ror:1 row_mask:0xf bank_mask:0xf
	v_mov_b32_e32 v104, v97
	v_mov_b32_dpp v105, v47 row_ror:1 row_mask:0xf bank_mask:0xf
	v_mov_b32_e32 v106, v97
	v_mov_b32_e32 v82, v97
	v_mov_b32_e32 v83, v97
	v_mov_b32_dpp v84, v46 row_ror:15 row_mask:0xf bank_mask:0xf
	v_mov_b32_dpp v85, v47 row_ror:15 row_mask:0xf bank_mask:0xf
	v_mov_b32_dpp v96, v44 row_ror:1 row_mask:0xf bank_mask:0xf
	v_mov_b32_e32 v94, v97
	v_mov_b32_dpp v98, v45 row_ror:1 row_mask:0xf bank_mask:0xf
	v_mov_b32_e32 v95, v97
	v_mov_b32_dpp v104, v62 row_ror:15 row_mask:0xf bank_mask:0xf
	v_mov_b32_dpp v106, v63 row_ror:15 row_mask:0xf bank_mask:0xf
	v_cndmask_b32_e64 v87, v105, 0, s[10:11]
	v_cndmask_b32_e64 v86, v99, 0, s[10:11]
	v_mov_b32_dpp v82, v44 row_ror:15 row_mask:0xf bank_mask:0xf
	v_mov_b32_dpp v83, v45 row_ror:15 row_mask:0xf bank_mask:0xf
	v_mov_b32_dpp v94, v60 row_ror:15 row_mask:0xf bank_mask:0xf
	v_mov_b32_dpp v95, v61 row_ror:15 row_mask:0xf bank_mask:0xf
	v_cndmask_b32_e64 v85, v85, v106, s[12:13]
	v_cndmask_b32_e64 v84, v84, v104, s[12:13]
	v_cndmask_b32_e64 v89, v98, 0, s[10:11]
	v_cndmask_b32_e64 v88, v96, 0, s[10:11]
	v_mov_b32_e32 v107, v97
	v_mov_b32_e32 v108, v97
	v_mov_b32_e32 v109, v97
	v_mov_b32_e32 v110, v97
	v_mov_b32_e32 v111, v97
	v_mov_b32_e32 v113, v97
	v_cndmask_b32_e64 v83, v83, v95, s[12:13]
	v_cndmask_b32_e64 v82, v82, v94, s[12:13]
	v_mov_b32_dpp v107, v60 row_ror:1 row_mask:0xf bank_mask:0xf
	v_mov_b32_dpp v108, v56 row_ror:15 row_mask:0xf bank_mask:0xf
	v_mov_b32_dpp v109, v61 row_ror:1 row_mask:0xf bank_mask:0xf
	v_mov_b32_dpp v110, v57 row_ror:15 row_mask:0xf bank_mask:0xf
	v_mov_b32_dpp v111, v62 row_ror:1 row_mask:0xf bank_mask:0xf
	v_mov_b32_e32 v112, v97
	v_mov_b32_dpp v113, v63 row_ror:1 row_mask:0xf bank_mask:0xf
	v_mov_b32_e32 v114, v97
	v_mov_b32_dpp v112, v58 row_ror:15 row_mask:0xf bank_mask:0xf
	v_mov_b32_e32 v115, v97
	v_mov_b32_dpp v114, v59 row_ror:15 row_mask:0xf bank_mask:0xf
	v_mov_b32_e32 v117, v97
	v_mov_b32_dpp v115, v58 row_ror:1 row_mask:0xf bank_mask:0xf
	v_mov_b32_e32 v116, v97
	v_mov_b32_dpp v117, v59 row_ror:1 row_mask:0xf bank_mask:0xf
	v_mov_b32_e32 v118, v97
	v_mov_b32_dpp v116, v42 row_ror:15 row_mask:0xf bank_mask:0xf
	s_waitcnt lgkmcnt(3)
	v_pk_mul_f32 v[86:87], v[70:71], v[86:87]
	v_pk_mul_f32 v[88:89], v[68:69], v[88:89]
	s_waitcnt lgkmcnt(2)
	v_pk_fma_f32 v[86:87], v[46:47], v[66:67], v[86:87]
	s_waitcnt lgkmcnt(0)
; #define DPP_UP(v) __int_as_float(__builtin_amdgcn_update_dpp(0, __float_as_int(v), 0x121, 0xf, 0xf, false))
; #define DPP_DN(v) __int_as_float(__builtin_amdgcn_update_dpp(0, __float_as_int(v), 0x12F, 0xf, 0xf, false))
;     __device__ __forceinline__ void operator()(const f32x4 (&acc)[2][2][4][2], const Unit& u, int wr, int wc, int fr_in, int fq_in) const {
;     ...
;                     const f32x4 k0 = *(const f32x4*)(fk + co + ch), k1 = *(const f32x4*)(fk + DFF2 + co + ch), k2 = *(const f32x4*)(fk + 2 * DFF2 + co + ch), bb = *(const f32x4*)(fb + co + ch);
;                     f32x4 up_prev = (f32x4){0.f, 0.f, 0.f, 0.f}, up_cur, dn_cur, dn_next;
; #pragma unroll
;                     for (int j = 0; j < 4; ++j) dn_cur[j] = DPP_DN(acc[ai][pass][0][n][j]);
; #pragma unroll
;                     for (int m = 0; m < 4; ++m) {
;                         const f32x4 xv = acc[ai][pass][m][n];
; #pragma unroll
;                         for (int j = 0; j < 4; ++j) { up_cur[j] = DPP_UP(xv[j]); dn_next[j] = (m < 3) ? DPP_DN(acc[ai][pass][m < 3 ? m + 1 : 3][n][j]) : 0.f; }
;                         const f32x4 xp = f0 ? up_prev : up_cur, xn = f15 ? dn_next : dn_cur;
;                         const f32x4 c = (k0 * xp + k1 * xv) + (k2 * xn + bb);
;                         if (pass == 0) o[m] = c;
;                         else { f32x4 e;
; #pragma unroll
;                             for (int j = 0; j < 4; ++j) e[j] = __builtin_amdgcn_rcpf(1.0f + __builtin_amdgcn_exp2f(c[j] * -1.4426950408889634f));
;                             o[m] = o[m] * (c * e); }
;                         up_prev = up_cur; dn_cur = dn_next; }
	v_pk_fma_f32 v[84:85], v[74:75], v[84:85], v[78:79]
	v_pk_fma_f32 v[82:83], v[72:73], v[82:83], v[76:77]
	v_pk_fma_f32 v[88:89], v[44:45], v[64:65], v[88:89]
	v_pk_add_f32 v[84:85], v[86:87], v[84:85]
	v_cndmask_b32_e64 v87, v95, v110, s[12:13]
	v_cndmask_b32_e64 v86, v94, v108, s[12:13]
	v_cndmask_b32_e64 v95, v113, v105, s[10:11]
	v_cndmask_b32_e64 v94, v111, v99, s[10:11]
	v_cndmask_b32_e64 v99, v109, v98, s[10:11]
	v_cndmask_b32_e64 v98, v107, v96, s[10:11]
	v_pk_add_f32 v[82:83], v[88:89], v[82:83]
	v_cndmask_b32_e64 v89, v106, v114, s[12:13]
	v_cndmask_b32_e64 v88, v104, v112, s[12:13]
	v_pk_mul_f32 v[98:99], v[68:69], v[98:99]
	v_pk_mul_f32 v[94:95], v[70:71], v[94:95]
	v_mov_b32_e32 v96, v97
	v_mov_b32_e32 v105, v97
	v_pk_fma_f32 v[88:89], v[74:75], v[88:89], v[78:79]
	v_pk_fma_f32 v[86:87], v[72:73], v[86:87], v[76:77]
	v_pk_fma_f32 v[62:63], v[62:63], v[66:67], v[94:95]
	v_pk_fma_f32 v[60:61], v[60:61], v[64:65], v[98:99]
	v_mov_b32_dpp v96, v56 row_ror:1 row_mask:0xf bank_mask:0xf
	v_mov_b32_e32 v104, v97
	v_mov_b32_dpp v105, v57 row_ror:1 row_mask:0xf bank_mask:0xf
	v_mov_b32_e32 v106, v97
	v_pk_add_f32 v[94:95], v[60:61], v[86:87]
	v_pk_add_f32 v[98:99], v[62:63], v[88:89]
	v_mov_b32_dpp v104, v40 row_ror:15 row_mask:0xf bank_mask:0xf
	v_mov_b32_dpp v106, v41 row_ror:15 row_mask:0xf bank_mask:0xf
	v_mov_b32_dpp v118, v43 row_ror:15 row_mask:0xf bank_mask:0xf
	v_cndmask_b32_e64 v87, v117, v113, s[10:11]
	v_cndmask_b32_e64 v86, v115, v111, s[10:11]
	v_cndmask_b32_e64 v89, v105, v109, s[10:11]
	v_cndmask_b32_e64 v88, v96, v107, s[10:11]
	v_cndmask_b32_e64 v61, v110, v106, s[12:13]
	v_cndmask_b32_e64 v60, v108, v104, s[12:13]
	v_cndmask_b32_e64 v63, v114, v118, s[12:13]
	v_cndmask_b32_e64 v62, v112, v116, s[12:13]
	v_pk_mul_f32 v[88:89], v[68:69], v[88:89]
	v_pk_mul_f32 v[86:87], v[70:71], v[86:87]
	v_pk_fma_f32 v[62:63], v[74:75], v[62:63], v[78:79]
	v_pk_fma_f32 v[60:61], v[72:73], v[60:61], v[76:77]
	v_pk_fma_f32 v[58:59], v[58:59], v[66:67], v[86:87]
	v_pk_fma_f32 v[56:57], v[56:57], v[64:65], v[88:89]
	v_pk_add_f32 v[88:89], v[58:59], v[62:63]
	v_pk_add_f32 v[86:87], v[56:57], v[60:61]
	v_mov_b32_e32 v62, v97
	v_mov_b32_e32 v63, v97
	v_mov_b32_e32 v60, v97
	v_mov_b32_e32 v61, v97
	v_mov_b32_dpp v62, v40 row_ror:1 row_mask:0xf bank_mask:0xf
	v_mov_b32_dpp v63, v41 row_ror:1 row_mask:0xf bank_mask:0xf
	v_mov_b32_dpp v60, v42 row_ror:1 row_mask:0xf bank_mask:0xf
	v_mov_b32_dpp v61, v43 row_ror:1 row_mask:0xf bank_mask:0xf
	v_cndmask_b32_e64 v61, v61, v117, s[10:11]
	v_cndmask_b32_e64 v60, v60, v115, s[10:11]
	v_cndmask_b32_e64 v63, v63, v105, s[10:11]
	v_cndmask_b32_e64 v62, v62, v96, s[10:11]
	v_cndmask_b32_e64 v57, v106, 0, s[12:13]
	v_cndmask_b32_e64 v56, v104, 0, s[12:13]
	v_cndmask_b32_e64 v59, v118, 0, s[12:13]
	v_cndmask_b32_e64 v58, v116, 0, s[12:13]
	v_pk_mul_f32 v[62:63], v[68:69], v[62:63]
	v_pk_mul_f32 v[60:61], v[70:71], v[60:61]
	v_pk_fma_f32 v[58:59], v[74:75], v[58:59], v[78:79]
	v_pk_fma_f32 v[56:57], v[72:73], v[56:57], v[76:77]
	v_pk_fma_f32 v[60:61], v[42:43], v[66:67], v[60:61]
	v_pk_fma_f32 v[62:63], v[40:41], v[64:65], v[62:63]
	v_pk_add_f32 v[74:75], v[58:59], v[60:61]
	v_pk_add_f32 v[72:73], v[56:57], v[62:63]
	ds_read_b128 v[60:63], v213 offset:256
	ds_read_b128 v[56:59], v213 offset:320
	ds_read_b128 v[64:67], v213 offset:384
	ds_read_b128 v[68:71], v213 offset:448
	v_mov_b32_e32 v96, v97
	v_mov_b32_e32 v101, v97
	v_mov_b32_e32 v103, v97
	v_mov_b32_e32 v105, v97
	v_mov_b32_e32 v78, v97
	v_mov_b32_e32 v79, v97
	v_mov_b32_e32 v76, v97
	v_mov_b32_e32 v77, v97
	v_mov_b32_dpp v96, v36 row_ror:1 row_mask:0xf bank_mask:0xf
	v_mov_b32_e32 v100, v97
	v_mov_b32_dpp v101, v37 row_ror:1 row_mask:0xf bank_mask:0xf
	v_mov_b32_e32 v102, v97
	v_mov_b32_dpp v103, v38 row_ror:1 row_mask:0xf bank_mask:0xf
	v_mov_b32_e32 v104, v97
	v_mov_b32_dpp v105, v39 row_ror:1 row_mask:0xf bank_mask:0xf
	v_mov_b32_e32 v106, v97
	v_mov_b32_dpp v78, v36 row_ror:15 row_mask:0xf bank_mask:0xf
	v_mov_b32_dpp v79, v37 row_ror:15 row_mask:0xf bank_mask:0xf
	v_mov_b32_dpp v76, v38 row_ror:15 row_mask:0xf bank_mask:0xf
	v_mov_b32_dpp v77, v39 row_ror:15 row_mask:0xf bank_mask:0xf
	v_mov_b32_dpp v100, v52 row_ror:15 row_mask:0xf bank_mask:0xf
	v_mov_b32_dpp v102, v53 row_ror:15 row_mask:0xf bank_mask:0xf
	v_mov_b32_dpp v104, v54 row_ror:15 row_mask:0xf bank_mask:0xf
	v_mov_b32_dpp v106, v55 row_ror:15 row_mask:0xf bank_mask:0xf
	v_cndmask_b32_e64 v91, v101, 0, s[10:11]
	v_cndmask_b32_e64 v90, v96, 0, s[10:11]
	v_cndmask_b32_e64 v93, v105, 0, s[10:11]
	v_cndmask_b32_e64 v92, v103, 0, s[10:11]
	v_cndmask_b32_e64 v77, v77, v106, s[12:13]
	v_cndmask_b32_e64 v76, v76, v104, s[12:13]
	v_cndmask_b32_e64 v79, v79, v102, s[12:13]
	v_cndmask_b32_e64 v78, v78, v100, s[12:13]
	v_mov_b32_e32 v107, v97
	v_mov_b32_e32 v109, v97
	v_mov_b32_e32 v111, v97
	v_mov_b32_e32 v113, v97
	v_mov_b32_dpp v107, v52 row_ror:1 row_mask:0xf bank_mask:0xf
	v_mov_b32_e32 v108, v97
	v_mov_b32_dpp v109, v53 row_ror:1 row_mask:0xf bank_mask:0xf
	v_mov_b32_e32 v110, v97
	v_mov_b32_dpp v111, v54 row_ror:1 row_mask:0xf bank_mask:0xf
	v_mov_b32_e32 v112, v97
	v_mov_b32_dpp v113, v55 row_ror:1 row_mask:0xf bank_mask:0xf
	v_mov_b32_e32 v114, v97
	v_mov_b32_dpp v108, v48 row_ror:15 row_mask:0xf bank_mask:0xf
	v_mov_b32_dpp v110, v49 row_ror:15 row_mask:0xf bank_mask:0xf
	v_mov_b32_dpp v112, v50 row_ror:15 row_mask:0xf bank_mask:0xf
	v_mov_b32_dpp v114, v51 row_ror:15 row_mask:0xf bank_mask:0xf
	s_waitcnt lgkmcnt(3)
	v_pk_mul_f32 v[92:93], v[62:63], v[92:93]
	v_pk_mul_f32 v[90:91], v[60:61], v[90:91]
	s_waitcnt lgkmcnt(2)
	v_pk_fma_f32 v[92:93], v[38:39], v[58:59], v[92:93]
	s_waitcnt lgkmcnt(0)
; __device__ __forceinline__ unsigned cvt_pk_bf16(float lo, float hi) { unsigned r; asm volatile("v_cvt_pk_bf16_f32 %0, %1, %2" : "=v"(r) : "v"(lo), "v"(hi)); return r; }
; #define DPP_UP(v) __int_as_float(__builtin_amdgcn_update_dpp(0, __float_as_int(v), 0x121, 0xf, 0xf, false))
; #define DPP_DN(v) __int_as_float(__builtin_amdgcn_update_dpp(0, __float_as_int(v), 0x12F, 0xf, 0xf, false))
;     __device__ __forceinline__ void operator()(const f32x4 (&acc)[2][2][4][2], const Unit& u, int wr, int wc, int fr_in, int fq_in) const {
;     ...
;                         for (int j = 0; j < 4; ++j) { up_cur[j] = DPP_UP(xv[j]); dn_next[j] = (m < 3) ? DPP_DN(acc[ai][pass][m < 3 ? m + 1 : 3][n][j]) : 0.f; }
;                         const f32x4 xp = f0 ? up_prev : up_cur, xn = f15 ? dn_next : dn_cur;
;                         const f32x4 c = (k0 * xp + k1 * xv) + (k2 * xn + bb);
;                         if (pass == 0) o[m] = c;
;                         else { f32x4 e;
; #pragma unroll
;                             for (int j = 0; j < 4; ++j) e[j] = __builtin_amdgcn_rcpf(1.0f + __builtin_amdgcn_exp2f(c[j] * -1.4426950408889634f));
;                             o[m] = o[m] * (c * e); }
;                         up_prev = up_cur; dn_cur = dn_next; }
;                 }
;                 if (n == 0) {
; #pragma unroll
;                     for (int m = 0; m < 4; ++m) { wlo[m].x = cvt_pk_bf16(o[m][0], o[m][1]); wlo[m].y = cvt_pk_bf16(o[m][2], o[m][3]); }
;                 } else {
; #pragma unroll
;                     for (int m = 0; m < 4; ++m) { u32x4 w; w.x = wlo[m].x; w.y = wlo[m].y; w.z = cvt_pk_bf16(o[m][0], o[m][1]); w.w = cvt_pk_bf16(o[m][2], o[m][3]);
;                         *(u32x4*)(base + off0 + (unsigned)(ai * HALF + m * 16) * (DFF * 2u)) = w; }
;                 }
;                 if (fr < 2 || fr >= 14) { const int k = fr < 2 ? fr : fr - 12;
;                     const f32x4 xv = fr < 2 ? acc[ai][0][0][n] : acc[ai][0][3][n], yv = fr < 2 ? acc[ai][1][0][n] : acc[ai][1][3][n];
;                     char* sp = sbase + (size_t)((2 * ai + wr) * 4 + k) * (DFF2 * 2) + (size_t)ch * 2;
;                     u32x2 a, b; a.x = cvt_pk_bf16(xv[0], xv[1]); a.y = cvt_pk_bf16(xv[2], xv[3]); b.x = cvt_pk_bf16(yv[0], yv[1]); b.y = cvt_pk_bf16(yv[2], yv[3]);
;                     *(u32x2*)sp = a; *(u32x2*)(sp + DFF * 2) = b; }
	v_pk_fma_f32 v[78:79], v[64:65], v[78:79], v[68:69]
	v_pk_fma_f32 v[76:77], v[66:67], v[76:77], v[70:71]
	v_pk_fma_f32 v[90:91], v[36:37], v[56:57], v[90:91]
	v_pk_add_f32 v[76:77], v[92:93], v[76:77]
	v_pk_add_f32 v[78:79], v[90:91], v[78:79]
	v_mul_f32_e32 v92, 0xbfb8aa3b, v76
	v_mul_f32_e32 v90, 0xbfb8aa3b, v78
	v_mul_f32_e32 v91, 0xbfb8aa3b, v79
	v_mul_f32_e32 v93, 0xbfb8aa3b, v77
	v_exp_f32_e32 v90, v90
	v_exp_f32_e32 v91, v91
	v_exp_f32_e32 v92, v92
	v_exp_f32_e32 v93, v93
	v_add_f32_e32 v90, 1.0, v90
	v_add_f32_e32 v91, 1.0, v91
	v_add_f32_e32 v92, 1.0, v92
	v_add_f32_e32 v93, 1.0, v93
	v_rcp_f32_e32 v90, v90
	v_rcp_f32_e32 v91, v91
	v_rcp_f32_e32 v92, v92
	v_rcp_f32_e32 v93, v93
	v_pk_mul_f32 v[78:79], v[78:79], v[90:91]
	v_cndmask_b32_e64 v91, v109, v101, s[10:11]
	v_pk_mul_f32 v[76:77], v[76:77], v[92:93]
	v_cndmask_b32_e64 v90, v107, v96, s[10:11]
	v_cndmask_b32_e64 v93, v113, v105, s[10:11]
	v_cndmask_b32_e64 v92, v111, v103, s[10:11]
	v_pk_mul_f32 v[76:77], v[84:85], v[76:77]
	v_pk_mul_f32 v[78:79], v[82:83], v[78:79]
	v_cndmask_b32_e64 v83, v106, v114, s[12:13]
	v_cndmask_b32_e64 v82, v104, v112, s[12:13]
	v_cndmask_b32_e64 v85, v102, v110, s[12:13]
	v_cndmask_b32_e64 v84, v100, v108, s[12:13]
	v_pk_mul_f32 v[92:93], v[62:63], v[92:93]
	v_pk_mul_f32 v[90:91], v[60:61], v[90:91]
	v_pk_fma_f32 v[84:85], v[64:65], v[84:85], v[68:69]
	v_pk_fma_f32 v[82:83], v[66:67], v[82:83], v[70:71]
	v_pk_fma_f32 v[52:53], v[52:53], v[56:57], v[90:91]
	v_pk_fma_f32 v[54:55], v[54:55], v[58:59], v[92:93]
	v_pk_add_f32 v[52:53], v[52:53], v[84:85]
	v_pk_add_f32 v[54:55], v[54:55], v[82:83]
	v_mul_f32_e32 v82, 0xbfb8aa3b, v52
	v_mul_f32_e32 v83, 0xbfb8aa3b, v53
	v_mul_f32_e32 v84, 0xbfb8aa3b, v54
	v_mul_f32_e32 v85, 0xbfb8aa3b, v55
	v_exp_f32_e32 v82, v82
	v_exp_f32_e32 v83, v83
	v_exp_f32_e32 v84, v84
	v_exp_f32_e32 v85, v85
	v_add_f32_e32 v82, 1.0, v82
	v_add_f32_e32 v83, 1.0, v83
	v_add_f32_e32 v84, 1.0, v84
	v_add_f32_e32 v85, 1.0, v85
	v_rcp_f32_e32 v82, v82
	v_rcp_f32_e32 v83, v83
	v_rcp_f32_e32 v84, v84
	v_rcp_f32_e32 v85, v85
	v_mov_b32_e32 v96, v97
	v_pk_mul_f32 v[52:53], v[52:53], v[82:83]
	v_mov_b32_e32 v101, v97
	v_pk_mul_f32 v[54:55], v[54:55], v[84:85]
	v_pk_mul_f32 v[52:53], v[94:95], v[52:53]
	v_pk_mul_f32 v[82:83], v[98:99], v[54:55]
	v_mov_b32_e32 v94, v97
	v_mov_b32_e32 v99, v97
	v_mov_b32_e32 v95, v97
	v_mov_b32_dpp v94, v48 row_ror:1 row_mask:0xf bank_mask:0xf
	v_mov_b32_dpp v96, v49 row_ror:1 row_mask:0xf bank_mask:0xf
	v_mov_b32_e32 v98, v97
	v_mov_b32_dpp v99, v50 row_ror:1 row_mask:0xf bank_mask:0xf
	v_mov_b32_e32 v100, v97
	v_mov_b32_dpp v101, v51 row_ror:1 row_mask:0xf bank_mask:0xf
	v_mov_b32_e32 v102, v97
	v_mov_b32_dpp v95, v32 row_ror:15 row_mask:0xf bank_mask:0xf
	v_mov_b32_dpp v98, v33 row_ror:15 row_mask:0xf bank_mask:0xf
	v_mov_b32_dpp v100, v34 row_ror:15 row_mask:0xf bank_mask:0xf
	v_mov_b32_dpp v102, v35 row_ror:15 row_mask:0xf bank_mask:0xf
	v_cndmask_b32_e64 v91, v96, v109, s[10:11]
	v_cndmask_b32_e64 v90, v94, v107, s[10:11]
	v_cndmask_b32_e64 v93, v101, v113, s[10:11]
	v_cndmask_b32_e64 v92, v99, v111, s[10:11]
	v_cndmask_b32_e64 v55, v114, v102, s[12:13]
	v_cndmask_b32_e64 v54, v112, v100, s[12:13]
	v_cndmask_b32_e64 v85, v110, v98, s[12:13]
	v_cndmask_b32_e64 v84, v108, v95, s[12:13]
	v_pk_mul_f32 v[92:93], v[62:63], v[92:93]
	v_pk_mul_f32 v[90:91], v[60:61], v[90:91]
	v_pk_fma_f32 v[84:85], v[64:65], v[84:85], v[68:69]
	v_pk_fma_f32 v[54:55], v[66:67], v[54:55], v[70:71]
	v_pk_fma_f32 v[48:49], v[48:49], v[56:57], v[90:91]
	v_pk_fma_f32 v[50:51], v[50:51], v[58:59], v[92:93]
	v_pk_add_f32 v[48:49], v[48:49], v[84:85]
	v_pk_add_f32 v[50:51], v[50:51], v[54:55]
	v_mul_f32_e32 v54, 0xbfb8aa3b, v48
	v_mul_f32_e32 v55, 0xbfb8aa3b, v49
	v_mul_f32_e32 v84, 0xbfb8aa3b, v50
	v_mul_f32_e32 v85, 0xbfb8aa3b, v51
	v_exp_f32_e32 v54, v54
	v_exp_f32_e32 v55, v55
	v_exp_f32_e32 v84, v84
	v_exp_f32_e32 v85, v85
	v_add_f32_e32 v54, 1.0, v54
	v_add_f32_e32 v55, 1.0, v55
	v_add_f32_e32 v84, 1.0, v84
	v_add_f32_e32 v85, 1.0, v85
	v_rcp_f32_e32 v54, v54
	v_rcp_f32_e32 v55, v55
	v_rcp_f32_e32 v84, v84
	v_rcp_f32_e32 v85, v85
	v_pk_mul_f32 v[48:49], v[48:49], v[54:55]
	s_nop 0
	v_pk_mul_f32 v[48:49], v[86:87], v[48:49]
	v_pk_mul_f32 v[50:51], v[50:51], v[84:85]
	v_mov_b32_e32 v86, v97
	v_pk_mul_f32 v[84:85], v[88:89], v[50:51]
	v_mov_b32_e32 v87, v97
	v_mov_b32_e32 v88, v97
	v_mov_b32_e32 v89, v97
	v_mov_b32_dpp v86, v32 row_ror:1 row_mask:0xf bank_mask:0xf
	v_mov_b32_dpp v87, v33 row_ror:1 row_mask:0xf bank_mask:0xf
	v_mov_b32_dpp v88, v34 row_ror:1 row_mask:0xf bank_mask:0xf
	v_mov_b32_dpp v89, v35 row_ror:1 row_mask:0xf bank_mask:0xf
	v_cndmask_b32_e64 v51, v102, 0, s[12:13]
	v_cndmask_b32_e64 v50, v100, 0, s[12:13]
	v_cndmask_b32_e64 v55, v98, 0, s[12:13]
	v_cndmask_b32_e64 v54, v95, 0, s[12:13]
	v_pk_fma_f32 v[54:55], v[64:65], v[54:55], v[68:69]
	v_pk_fma_f32 v[50:51], v[66:67], v[50:51], v[70:71]
	v_cndmask_b32_e64 v65, v87, v96, s[10:11]
	v_cndmask_b32_e64 v64, v86, v94, s[10:11]
	v_cndmask_b32_e64 v67, v89, v101, s[10:11]
	v_cndmask_b32_e64 v66, v88, v99, s[10:11]
	v_pk_mul_f32 v[62:63], v[62:63], v[66:67]
	v_pk_mul_f32 v[60:61], v[60:61], v[64:65]
	v_pk_fma_f32 v[58:59], v[34:35], v[58:59], v[62:63]
	v_pk_fma_f32 v[56:57], v[32:33], v[56:57], v[60:61]
	v_pk_add_f32 v[50:51], v[50:51], v[58:59]
	v_pk_add_f32 v[54:55], v[54:55], v[56:57]
	v_mul_f32_e32 v58, 0xbfb8aa3b, v50
	v_mul_f32_e32 v56, 0xbfb8aa3b, v54
	v_mul_f32_e32 v57, 0xbfb8aa3b, v55
	v_mul_f32_e32 v59, 0xbfb8aa3b, v51
	v_exp_f32_e32 v56, v56
	v_exp_f32_e32 v57, v57
	v_exp_f32_e32 v58, v58
	v_exp_f32_e32 v59, v59
	v_add_f32_e32 v56, 1.0, v56
	v_add_f32_e32 v57, 1.0, v57
	v_add_f32_e32 v58, 1.0, v58
	v_add_f32_e32 v59, 1.0, v59
	v_rcp_f32_e32 v56, v56
	v_rcp_f32_e32 v57, v57
	v_rcp_f32_e32 v58, v58
	v_rcp_f32_e32 v59, v59
	v_pk_mul_f32 v[54:55], v[54:55], v[56:57]
	v_pk_mul_f32 v[50:51], v[50:51], v[58:59]
	s_nop 0
	v_pk_mul_f32 v[56:57], v[74:75], v[50:51]
	v_pk_mul_f32 v[58:59], v[72:73], v[54:55]
	v_cvt_pk_bf16_f32 v54, v78, v79
	v_cvt_pk_bf16_f32 v55, v76, v77
	v_cvt_pk_bf16_f32 v52, v52, v53
	v_cvt_pk_bf16_f32 v53, v82, v83
	v_cvt_pk_bf16_f32 v50, v48, v49
	v_cvt_pk_bf16_f32 v51, v84, v85
	s_nop 0
	v_cvt_pk_bf16_f32 v48, v58, v59
	v_cvt_pk_bf16_f32 v49, v56, v57
	s_and_saveexec_b64 s[22:23], s[8:9]
	s_cbranch_execz .LBB0_1052
	v_cndmask_b32_e64 v36, v32, v36, s[6:7]
	v_cndmask_b32_e64 v37, v33, v37, s[6:7]
	v_lshl_add_u64 v[32:33], v[158:159], 1, v[80:81]
	v_cndmask_b32_e64 v42, v42, v46, s[6:7]
	v_cndmask_b32_e64 v43, v43, v47, s[6:7]
	v_cndmask_b32_e64 v40, v40, v44, s[6:7]
	v_cndmask_b32_e64 v41, v41, v45, s[6:7]
	v_cndmask_b32_e64 v38, v34, v38, s[6:7]
	v_cndmask_b32_e64 v39, v35, v39, s[6:7]
	v_cvt_pk_bf16_f32 v34, v40, v41
	v_cvt_pk_bf16_f32 v35, v42, v43
	v_cvt_pk_bf16_f32 v36, v36, v37
	v_cvt_pk_bf16_f32 v37, v38, v39
	global_store_dwordx2 v[32:33], v[34:35], off
	v_add_co_u32_e32 v32, vcc, 0x1000, v32
	s_nop 1
	v_addc_co_u32_e32 v33, vcc, 0, v33, vcc
	global_store_dwordx2 v[32:33], v[36:37], off offset:1536
; #define DPP_UP(v) __int_as_float(__builtin_amdgcn_update_dpp(0, __float_as_int(v), 0x121, 0xf, 0xf, false))
; #define DPP_DN(v) __int_as_float(__builtin_amdgcn_update_dpp(0, __float_as_int(v), 0x12F, 0xf, 0xf, false))
;     __device__ __forceinline__ void operator()(const f32x4 (&acc)[2][2][4][2], const Unit& u, int wr, int wc, int fr_in, int fq_in) const {
;     ...
;                 const int ch = ch0 + 4 * n;
; #pragma unroll
;                 for (int pass = 0; pass < 2; ++pass) {
;                     const int co = pass ? DFF : 0;
;                     const f32x4 k0 = *(const f32x4*)(fk + co + ch), k1 = *(const f32x4*)(fk + DFF2 + co + ch), k2 = *(const f32x4*)(fk + 2 * DFF2 + co + ch), bb = *(const f32x4*)(fb + co + ch);
;                     f32x4 up_prev = (f32x4){0.f, 0.f, 0.f, 0.f}, up_cur, dn_cur, dn_next;
; #pragma unroll
;                     for (int j = 0; j < 4; ++j) dn_cur[j] = DPP_DN(acc[ai][pass][0][n][j]);
; #pragma unroll
;                     for (int m = 0; m < 4; ++m) {
;                         const f32x4 xv = acc[ai][pass][m][n];
; #pragma unroll
;                         for (int j = 0; j < 4; ++j) { up_cur[j] = DPP_UP(xv[j]); dn_next[j] = (m < 3) ? DPP_DN(acc[ai][pass][m < 3 ? m + 1 : 3][n][j]) : 0.f; }
;                         const f32x4 xp = f0 ? up_prev : up_cur, xn = f15 ? dn_next : dn_cur;
;                         const f32x4 c = (k0 * xp + k1 * xv) + (k2 * xn + bb);
;                         if (pass == 0) o[m] = c;
;                         else { f32x4 e;
; #pragma unroll
;                             for (int j = 0; j < 4; ++j) e[j] = __builtin_amdgcn_rcpf(1.0f + __builtin_amdgcn_exp2f(c[j] * -1.4426950408889634f));
;                             o[m] = o[m] * (c * e); }
;                         up_prev = up_cur; dn_cur = dn_next; }
.LBB0_1052:
	s_or_b64 exec, exec, s[22:23]
	v_lshl_add_u64 v[32:33], v[160:161], 0, 16
	v_lshl_add_u64 v[44:45], v[162:163], 0, 16
	ds_read_b128 v[36:39], v213 offset:512
	s_nop 0
	ds_read_b128 v[32:35], v213 offset:576
	ds_read_b128 v[40:43], v213 offset:640
	s_nop 0
	ds_read_b128 v[44:47], v213 offset:704
	v_mov_b32_e32 v76, v97
	v_mov_b32_e32 v78, v97
	v_mov_b32_e32 v58, v97
	v_mov_b32_e32 v59, v97
	v_mov_b32_e32 v70, v97
	v_mov_b32_e32 v71, v97
	v_mov_b32_dpp v76, v2 row_ror:1 row_mask:0xf bank_mask:0xf
	v_mov_b32_e32 v77, v97
	v_mov_b32_dpp v78, v3 row_ror:1 row_mask:0xf bank_mask:0xf
	v_mov_b32_e32 v79, v97
	v_mov_b32_e32 v56, v97
	v_mov_b32_e32 v57, v97
	v_mov_b32_dpp v58, v2 row_ror:15 row_mask:0xf bank_mask:0xf
	v_mov_b32_dpp v59, v3 row_ror:15 row_mask:0xf bank_mask:0xf
	v_mov_b32_dpp v70, v0 row_ror:1 row_mask:0xf bank_mask:0xf
	v_mov_b32_e32 v68, v97
	v_mov_b32_dpp v71, v1 row_ror:1 row_mask:0xf bank_mask:0xf
	v_mov_b32_e32 v69, v97
	v_mov_b32_dpp v77, v30 row_ror:15 row_mask:0xf bank_mask:0xf
	v_mov_b32_dpp v79, v31 row_ror:15 row_mask:0xf bank_mask:0xf
	v_cndmask_b32_e64 v61, v78, 0, s[10:11]
	v_cndmask_b32_e64 v60, v76, 0, s[10:11]
	v_mov_b32_dpp v56, v0 row_ror:15 row_mask:0xf bank_mask:0xf
	v_mov_b32_dpp v57, v1 row_ror:15 row_mask:0xf bank_mask:0xf
	v_mov_b32_dpp v68, v28 row_ror:15 row_mask:0xf bank_mask:0xf
	v_mov_b32_dpp v69, v29 row_ror:15 row_mask:0xf bank_mask:0xf
	v_cndmask_b32_e64 v59, v59, v79, s[12:13]
	v_cndmask_b32_e64 v58, v58, v77, s[12:13]
	v_cndmask_b32_e64 v63, v71, 0, s[10:11]
	v_cndmask_b32_e64 v62, v70, 0, s[10:11]
	v_mov_b32_e32 v82, v97
	v_mov_b32_e32 v83, v97
	v_mov_b32_e32 v84, v97
	v_mov_b32_e32 v85, v97
	v_mov_b32_e32 v86, v97
	v_mov_b32_e32 v88, v97
	v_cndmask_b32_e64 v57, v57, v69, s[12:13]
	v_cndmask_b32_e64 v56, v56, v68, s[12:13]
	v_mov_b32_dpp v82, v28 row_ror:1 row_mask:0xf bank_mask:0xf
	v_mov_b32_dpp v83, v24 row_ror:15 row_mask:0xf bank_mask:0xf
	v_mov_b32_dpp v84, v29 row_ror:1 row_mask:0xf bank_mask:0xf
	v_mov_b32_dpp v85, v25 row_ror:15 row_mask:0xf bank_mask:0xf
	v_mov_b32_dpp v86, v30 row_ror:1 row_mask:0xf bank_mask:0xf
	v_mov_b32_e32 v87, v97
	v_mov_b32_dpp v88, v31 row_ror:1 row_mask:0xf bank_mask:0xf
	v_mov_b32_e32 v89, v97
	v_mov_b32_dpp v87, v26 row_ror:15 row_mask:0xf bank_mask:0xf
	v_cndmask_b32_e64 v71, v84, v71, s[10:11]
	v_mov_b32_dpp v89, v27 row_ror:15 row_mask:0xf bank_mask:0xf
	v_cndmask_b32_e64 v70, v82, v70, s[10:11]
	v_mov_b32_e32 v90, v97
	v_mov_b32_e32 v92, v97
	v_mov_b32_e32 v91, v97
	v_mov_b32_dpp v90, v26 row_ror:1 row_mask:0xf bank_mask:0xf
	v_mov_b32_dpp v92, v27 row_ror:1 row_mask:0xf bank_mask:0xf
	v_mov_b32_e32 v93, v97
	v_mov_b32_dpp v91, v6 row_ror:15 row_mask:0xf bank_mask:0xf
	s_mov_b64 s[22:23], 0x2c10
	v_mov_b32_dpp v93, v7 row_ror:15 row_mask:0xf bank_mask:0xf
	v_lshl_add_u64 v[72:73], v[160:161], 0, s[22:23]
	s_mov_b64 s[0:1], 0x2c00
	v_lshl_add_u64 v[74:75], v[130:131], 0, s[0:1]
	v_lshl_add_u64 v[64:65], v[128:129], 0, s[0:1]
	v_lshl_add_u64 v[66:67], v[162:163], 0, s[22:23]
	s_mov_b32 s0, 0xb0000
	s_waitcnt lgkmcnt(3)
	v_pk_mul_f32 v[60:61], v[38:39], v[60:61]
	v_pk_mul_f32 v[62:63], v[36:37], v[62:63]
	s_waitcnt lgkmcnt(2)
	v_pk_fma_f32 v[60:61], v[2:3], v[34:35], v[60:61]
	s_waitcnt lgkmcnt(0)
	v_pk_fma_f32 v[58:59], v[42:43], v[58:59], v[46:47]
	v_pk_fma_f32 v[56:57], v[40:41], v[56:57], v[44:45]
	v_pk_fma_f32 v[62:63], v[0:1], v[32:33], v[62:63]
	v_pk_add_f32 v[58:59], v[60:61], v[58:59]
	v_cndmask_b32_e64 v61, v69, v85, s[12:13]
	v_cndmask_b32_e64 v60, v68, v83, s[12:13]
	v_cndmask_b32_e64 v69, v88, v78, s[10:11]
	v_cndmask_b32_e64 v68, v86, v76, s[10:11]
	v_mov_b32_e32 v76, v97
	v_mov_b32_e32 v78, v97
	v_pk_add_f32 v[56:57], v[62:63], v[56:57]
	v_cndmask_b32_e64 v63, v79, v89, s[12:13]
	v_cndmask_b32_e64 v62, v77, v87, s[12:13]
	v_pk_mul_f32 v[70:71], v[36:37], v[70:71]
	v_pk_mul_f32 v[68:69], v[38:39], v[68:69]
	v_mov_b32_dpp v76, v24 row_ror:1 row_mask:0xf bank_mask:0xf
	v_mov_b32_e32 v77, v97
	v_mov_b32_dpp v78, v25 row_ror:1 row_mask:0xf bank_mask:0xf
	v_mov_b32_e32 v79, v97
	v_pk_fma_f32 v[62:63], v[42:43], v[62:63], v[46:47]
	v_pk_fma_f32 v[60:61], v[40:41], v[60:61], v[44:45]
	v_pk_fma_f32 v[30:31], v[30:31], v[34:35], v[68:69]
	v_pk_fma_f32 v[28:29], v[28:29], v[32:33], v[70:71]
	v_mov_b32_dpp v77, v4 row_ror:15 row_mask:0xf bank_mask:0xf
	v_mov_b32_dpp v79, v5 row_ror:15 row_mask:0xf bank_mask:0xf
	v_cndmask_b32_e64 v69, v92, v88, s[10:11]
	v_cndmask_b32_e64 v68, v90, v86, s[10:11]
	v_cndmask_b32_e64 v71, v78, v84, s[10:11]
	v_cndmask_b32_e64 v70, v76, v82, s[10:11]
	v_pk_add_f32 v[60:61], v[28:29], v[60:61]
	v_pk_add_f32 v[62:63], v[30:31], v[62:63]
	v_cndmask_b32_e64 v29, v85, v79, s[12:13]
	v_cndmask_b32_e64 v28, v83, v77, s[12:13]
	v_cndmask_b32_e64 v31, v89, v93, s[12:13]
	v_cndmask_b32_e64 v30, v87, v91, s[12:13]
	v_pk_mul_f32 v[70:71], v[36:37], v[70:71]
	v_pk_mul_f32 v[68:69], v[38:39], v[68:69]
	v_pk_fma_f32 v[30:31], v[42:43], v[30:31], v[46:47]
	v_pk_fma_f32 v[28:29], v[40:41], v[28:29], v[44:45]
	v_pk_fma_f32 v[26:27], v[26:27], v[34:35], v[68:69]
	v_pk_fma_f32 v[24:25], v[24:25], v[32:33], v[70:71]
	v_pk_add_f32 v[70:71], v[26:27], v[30:31]
	v_pk_add_f32 v[68:69], v[24:25], v[28:29]
	v_mov_b32_e32 v30, v97
	v_mov_b32_e32 v31, v97
	v_mov_b32_e32 v28, v97
	v_mov_b32_e32 v29, v97
	v_mov_b32_dpp v30, v4 row_ror:1 row_mask:0xf bank_mask:0xf
	v_mov_b32_dpp v31, v5 row_ror:1 row_mask:0xf bank_mask:0xf
	v_mov_b32_dpp v28, v6 row_ror:1 row_mask:0xf bank_mask:0xf
	v_mov_b32_dpp v29, v7 row_ror:1 row_mask:0xf bank_mask:0xf
	v_cndmask_b32_e64 v29, v29, v92, s[10:11]
	v_cndmask_b32_e64 v28, v28, v90, s[10:11]
; #define DPP_UP(v) __int_as_float(__builtin_amdgcn_update_dpp(0, __float_as_int(v), 0x121, 0xf, 0xf, false))
; #define DPP_DN(v) __int_as_float(__builtin_amdgcn_update_dpp(0, __float_as_int(v), 0x12F, 0xf, 0xf, false))
;     __device__ __forceinline__ void operator()(const f32x4 (&acc)[2][2][4][2], const Unit& u, int wr, int wc, int fr_in, int fq_in) const {
;     ...
;                     const f32x4 k0 = *(const f32x4*)(fk + co + ch), k1 = *(const f32x4*)(fk + DFF2 + co + ch), k2 = *(const f32x4*)(fk + 2 * DFF2 + co + ch), bb = *(const f32x4*)(fb + co + ch);
;                     f32x4 up_prev = (f32x4){0.f, 0.f, 0.f, 0.f}, up_cur, dn_cur, dn_next;
; #pragma unroll
;                     for (int j = 0; j < 4; ++j) dn_cur[j] = DPP_DN(acc[ai][pass][0][n][j]);
; #pragma unroll
;                     for (int m = 0; m < 4; ++m) {
;                         const f32x4 xv = acc[ai][pass][m][n];
; #pragma unroll
;                         for (int j = 0; j < 4; ++j) { up_cur[j] = DPP_UP(xv[j]); dn_next[j] = (m < 3) ? DPP_DN(acc[ai][pass][m < 3 ? m + 1 : 3][n][j]) : 0.f; }
;                         const f32x4 xp = f0 ? up_prev : up_cur, xn = f15 ? dn_next : dn_cur;
;                         const f32x4 c = (k0 * xp + k1 * xv) + (k2 * xn + bb);
;                         if (pass == 0) o[m] = c;
;                         else { f32x4 e;
; #pragma unroll
;                             for (int j = 0; j < 4; ++j) e[j] = __builtin_amdgcn_rcpf(1.0f + __builtin_amdgcn_exp2f(c[j] * -1.4426950408889634f));
;                             o[m] = o[m] * (c * e); }
;                         up_prev = up_cur; dn_cur = dn_next; }
	v_cndmask_b32_e64 v31, v31, v78, s[10:11]
	v_cndmask_b32_e64 v30, v30, v76, s[10:11]
	v_cndmask_b32_e64 v25, v79, 0, s[12:13]
	v_cndmask_b32_e64 v24, v77, 0, s[12:13]
	v_cndmask_b32_e64 v27, v93, 0, s[12:13]
	v_cndmask_b32_e64 v26, v91, 0, s[12:13]
	v_pk_mul_f32 v[30:31], v[36:37], v[30:31]
	v_pk_mul_f32 v[28:29], v[38:39], v[28:29]
	v_pk_fma_f32 v[26:27], v[42:43], v[26:27], v[46:47]
	v_pk_fma_f32 v[24:25], v[40:41], v[24:25], v[44:45]
	v_pk_fma_f32 v[28:29], v[6:7], v[34:35], v[28:29]
	v_pk_fma_f32 v[30:31], v[4:5], v[32:33], v[30:31]
	v_pk_add_f32 v[42:43], v[26:27], v[28:29]
	v_pk_add_f32 v[40:41], v[24:25], v[30:31]
	ds_read_b128 v[28:31], v213 offset:768
	ds_read_b128 v[24:27], v213 offset:832
	ds_read_b128 v[32:35], v213 offset:896
	ds_read_b128 v[36:39], v213 offset:960
	v_mov_b32_e32 v72, v97
	v_mov_b32_e32 v74, v97
	v_mov_b32_e32 v76, v97
	v_mov_b32_e32 v78, v97
	v_mov_b32_e32 v46, v97
	v_mov_b32_e32 v47, v97
	v_mov_b32_e32 v44, v97
	v_mov_b32_e32 v45, v97
	v_mov_b32_dpp v72, v8 row_ror:1 row_mask:0xf bank_mask:0xf
	v_mov_b32_e32 v73, v97
	v_mov_b32_dpp v74, v9 row_ror:1 row_mask:0xf bank_mask:0xf
	v_mov_b32_e32 v75, v97
	v_mov_b32_dpp v76, v10 row_ror:1 row_mask:0xf bank_mask:0xf
	v_mov_b32_e32 v77, v97
	v_mov_b32_dpp v78, v11 row_ror:1 row_mask:0xf bank_mask:0xf
	v_mov_b32_e32 v79, v97
	v_mov_b32_dpp v46, v8 row_ror:15 row_mask:0xf bank_mask:0xf
	v_mov_b32_dpp v47, v9 row_ror:15 row_mask:0xf bank_mask:0xf
	v_mov_b32_dpp v44, v10 row_ror:15 row_mask:0xf bank_mask:0xf
	v_mov_b32_dpp v45, v11 row_ror:15 row_mask:0xf bank_mask:0xf
	v_mov_b32_dpp v73, v20 row_ror:15 row_mask:0xf bank_mask:0xf
	v_mov_b32_dpp v75, v21 row_ror:15 row_mask:0xf bank_mask:0xf
	v_mov_b32_dpp v77, v22 row_ror:15 row_mask:0xf bank_mask:0xf
	v_mov_b32_dpp v79, v23 row_ror:15 row_mask:0xf bank_mask:0xf
	v_cndmask_b32_e64 v65, v74, 0, s[10:11]
	v_cndmask_b32_e64 v64, v72, 0, s[10:11]
	v_cndmask_b32_e64 v67, v78, 0, s[10:11]
	v_cndmask_b32_e64 v66, v76, 0, s[10:11]
	v_cndmask_b32_e64 v45, v45, v79, s[12:13]
	v_cndmask_b32_e64 v44, v44, v77, s[12:13]
	v_cndmask_b32_e64 v47, v47, v75, s[12:13]
	v_cndmask_b32_e64 v46, v46, v73, s[12:13]
	v_mov_b32_e32 v82, v97
	v_mov_b32_e32 v84, v97
	v_mov_b32_e32 v86, v97
	v_mov_b32_e32 v88, v97
	v_mov_b32_dpp v82, v20 row_ror:1 row_mask:0xf bank_mask:0xf
	v_mov_b32_e32 v83, v97
	v_mov_b32_dpp v84, v21 row_ror:1 row_mask:0xf bank_mask:0xf
	v_mov_b32_e32 v85, v97
	v_mov_b32_dpp v86, v22 row_ror:1 row_mask:0xf bank_mask:0xf
	v_mov_b32_e32 v87, v97
	v_mov_b32_dpp v88, v23 row_ror:1 row_mask:0xf bank_mask:0xf
	v_mov_b32_e32 v89, v97
	v_mov_b32_dpp v83, v16 row_ror:15 row_mask:0xf bank_mask:0xf
	v_mov_b32_dpp v85, v17 row_ror:15 row_mask:0xf bank_mask:0xf
	v_mov_b32_dpp v87, v18 row_ror:15 row_mask:0xf bank_mask:0xf
	v_mov_b32_dpp v89, v19 row_ror:15 row_mask:0xf bank_mask:0xf
	s_waitcnt lgkmcnt(3)
	v_pk_mul_f32 v[66:67], v[30:31], v[66:67]
	v_pk_mul_f32 v[64:65], v[28:29], v[64:65]
	s_waitcnt lgkmcnt(2)
	v_pk_fma_f32 v[66:67], v[10:11], v[26:27], v[66:67]
	s_waitcnt lgkmcnt(0)
	v_pk_fma_f32 v[46:47], v[32:33], v[46:47], v[36:37]
	v_pk_fma_f32 v[44:45], v[34:35], v[44:45], v[38:39]
	v_pk_fma_f32 v[64:65], v[8:9], v[24:25], v[64:65]
	v_pk_add_f32 v[44:45], v[66:67], v[44:45]
	v_pk_add_f32 v[46:47], v[64:65], v[46:47]
	v_mul_f32_e32 v66, 0xbfb8aa3b, v44
	v_mul_f32_e32 v64, 0xbfb8aa3b, v46
	v_mul_f32_e32 v65, 0xbfb8aa3b, v47
	v_mul_f32_e32 v67, 0xbfb8aa3b, v45
	v_exp_f32_e32 v64, v64
	v_exp_f32_e32 v65, v65
	v_exp_f32_e32 v66, v66
	v_exp_f32_e32 v67, v67
	v_add_f32_e32 v64, 1.0, v64
	v_add_f32_e32 v65, 1.0, v65
	v_add_f32_e32 v66, 1.0, v66
	v_add_f32_e32 v67, 1.0, v67
	v_rcp_f32_e32 v64, v64
	v_rcp_f32_e32 v65, v65
	v_rcp_f32_e32 v66, v66
	v_rcp_f32_e32 v67, v67
	v_pk_mul_f32 v[46:47], v[46:47], v[64:65]
	v_cndmask_b32_e64 v65, v84, v74, s[10:11]
	v_pk_mul_f32 v[44:45], v[44:45], v[66:67]
	v_cndmask_b32_e64 v64, v82, v72, s[10:11]
	v_cndmask_b32_e64 v67, v88, v78, s[10:11]
	v_cndmask_b32_e64 v66, v86, v76, s[10:11]
	v_pk_mul_f32 v[44:45], v[58:59], v[44:45]
	v_pk_mul_f32 v[46:47], v[56:57], v[46:47]
	v_cndmask_b32_e64 v57, v79, v89, s[12:13]
	v_cndmask_b32_e64 v56, v77, v87, s[12:13]
	v_cndmask_b32_e64 v59, v75, v85, s[12:13]
	v_cndmask_b32_e64 v58, v73, v83, s[12:13]
	v_pk_mul_f32 v[66:67], v[30:31], v[66:67]
	v_pk_mul_f32 v[64:65], v[28:29], v[64:65]
	v_pk_fma_f32 v[58:59], v[32:33], v[58:59], v[36:37]
	v_pk_fma_f32 v[56:57], v[34:35], v[56:57], v[38:39]
	v_pk_fma_f32 v[20:21], v[20:21], v[24:25], v[64:65]
	v_pk_fma_f32 v[22:23], v[22:23], v[26:27], v[66:67]
	v_pk_add_f32 v[20:21], v[20:21], v[58:59]
	v_pk_add_f32 v[22:23], v[22:23], v[56:57]
	v_mul_f32_e32 v56, 0xbfb8aa3b, v20
	v_mul_f32_e32 v57, 0xbfb8aa3b, v21
	v_mul_f32_e32 v58, 0xbfb8aa3b, v22
	v_mul_f32_e32 v59, 0xbfb8aa3b, v23
	v_exp_f32_e32 v56, v56
	v_exp_f32_e32 v57, v57
	v_exp_f32_e32 v58, v58
	v_exp_f32_e32 v59, v59
	v_add_f32_e32 v56, 1.0, v56
	v_add_f32_e32 v57, 1.0, v57
	v_add_f32_e32 v58, 1.0, v58
	v_add_f32_e32 v59, 1.0, v59
	v_rcp_f32_e32 v56, v56
	v_rcp_f32_e32 v57, v57
	v_rcp_f32_e32 v58, v58
	v_rcp_f32_e32 v59, v59
	v_mov_b32_e32 v72, v97
	v_mov_b32_e32 v74, v97
	v_pk_mul_f32 v[56:57], v[20:21], v[56:57]
	v_pk_mul_f32 v[20:21], v[22:23], v[58:59]
	v_mov_b32_e32 v64, v97
	v_mov_b32_e32 v66, v97
; __device__ __forceinline__ unsigned cvt_pk_bf16(float lo, float hi) { unsigned r; asm volatile("v_cvt_pk_bf16_f32 %0, %1, %2" : "=v"(r) : "v"(lo), "v"(hi)); return r; }
; #define DPP_UP(v) __int_as_float(__builtin_amdgcn_update_dpp(0, __float_as_int(v), 0x121, 0xf, 0xf, false))
; #define DPP_DN(v) __int_as_float(__builtin_amdgcn_update_dpp(0, __float_as_int(v), 0x12F, 0xf, 0xf, false))
;     __device__ __forceinline__ void operator()(const f32x4 (&acc)[2][2][4][2], const Unit& u, int wr, int wc, int fr_in, int fq_in) const {
;     ...
;                         for (int j = 0; j < 4; ++j) { up_cur[j] = DPP_UP(xv[j]); dn_next[j] = (m < 3) ? DPP_DN(acc[ai][pass][m < 3 ? m + 1 : 3][n][j]) : 0.f; }
;                         const f32x4 xp = f0 ? up_prev : up_cur, xn = f15 ? dn_next : dn_cur;
;                         const f32x4 c = (k0 * xp + k1 * xv) + (k2 * xn + bb);
;                         if (pass == 0) o[m] = c;
;                         else { f32x4 e;
; #pragma unroll
;                             for (int j = 0; j < 4; ++j) e[j] = __builtin_amdgcn_rcpf(1.0f + __builtin_amdgcn_exp2f(c[j] * -1.4426950408889634f));
;                             o[m] = o[m] * (c * e); }
;                         up_prev = up_cur; dn_cur = dn_next; }
;                 }
;                 if (n == 0) {
; #pragma unroll
;                     for (int m = 0; m < 4; ++m) { wlo[m].x = cvt_pk_bf16(o[m][0], o[m][1]); wlo[m].y = cvt_pk_bf16(o[m][2], o[m][3]); }
;                 } else {
; #pragma unroll
;                     for (int m = 0; m < 4; ++m) { u32x4 w; w.x = wlo[m].x; w.y = wlo[m].y; w.z = cvt_pk_bf16(o[m][0], o[m][1]); w.w = cvt_pk_bf16(o[m][2], o[m][3]);
;                         *(u32x4*)(base + off0 + (unsigned)(ai * HALF + m * 16) * (DFF * 2u)) = w; }
;                 }
;                 if (fr < 2 || fr >= 14) { const int k = fr < 2 ? fr : fr - 12;
;                     const f32x4 xv = fr < 2 ? acc[ai][0][0][n] : acc[ai][0][3][n], yv = fr < 2 ? acc[ai][1][0][n] : acc[ai][1][3][n];
;                     char* sp = sbase + (size_t)((2 * ai + wr) * 4 + k) * (DFF2 * 2) + (size_t)ch * 2;
;                     u32x2 a, b; a.x = cvt_pk_bf16(xv[0], xv[1]); a.y = cvt_pk_bf16(xv[2], xv[3]); b.x = cvt_pk_bf16(yv[0], yv[1]); b.y = cvt_pk_bf16(yv[2], yv[3]);
;                     *(u32x2*)sp = a; *(u32x2*)(sp + DFF * 2) = b; }
	v_mov_b32_dpp v72, v18 row_ror:1 row_mask:0xf bank_mask:0xf
	v_mov_b32_e32 v73, v97
	v_mov_b32_dpp v74, v19 row_ror:1 row_mask:0xf bank_mask:0xf
	v_mov_b32_e32 v75, v97
	v_pk_mul_f32 v[20:21], v[62:63], v[20:21]
	v_mov_b32_dpp v64, v16 row_ror:1 row_mask:0xf bank_mask:0xf
	v_mov_b32_e32 v65, v97
	v_mov_b32_dpp v66, v17 row_ror:1 row_mask:0xf bank_mask:0xf
	v_mov_b32_e32 v67, v97
	v_mov_b32_dpp v73, v14 row_ror:15 row_mask:0xf bank_mask:0xf
	v_mov_b32_dpp v75, v15 row_ror:15 row_mask:0xf bank_mask:0xf
	v_cndmask_b32_e64 v63, v74, v88, s[10:11]
	v_cndmask_b32_e64 v62, v72, v86, s[10:11]
	v_pk_mul_f32 v[22:23], v[60:61], v[56:57]
	v_mov_b32_dpp v65, v12 row_ror:15 row_mask:0xf bank_mask:0xf
	v_mov_b32_dpp v67, v13 row_ror:15 row_mask:0xf bank_mask:0xf
	v_cndmask_b32_e64 v57, v89, v75, s[12:13]
	v_cndmask_b32_e64 v56, v87, v73, s[12:13]
	v_cndmask_b32_e64 v61, v66, v84, s[10:11]
	v_cndmask_b32_e64 v60, v64, v82, s[10:11]
	v_pk_mul_f32 v[62:63], v[30:31], v[62:63]
	v_cndmask_b32_e64 v59, v85, v67, s[12:13]
	v_cndmask_b32_e64 v58, v83, v65, s[12:13]
	v_pk_fma_f32 v[56:57], v[34:35], v[56:57], v[38:39]
	v_pk_mul_f32 v[60:61], v[28:29], v[60:61]
	v_pk_fma_f32 v[18:19], v[18:19], v[26:27], v[62:63]
	v_pk_fma_f32 v[58:59], v[32:33], v[58:59], v[36:37]
	v_pk_fma_f32 v[16:17], v[16:17], v[24:25], v[60:61]
	v_pk_add_f32 v[18:19], v[18:19], v[56:57]
	v_pk_add_f32 v[16:17], v[16:17], v[58:59]
	v_mul_f32_e32 v58, 0xbfb8aa3b, v18
	v_mul_f32_e32 v59, 0xbfb8aa3b, v19
	v_exp_f32_e32 v58, v58
	v_exp_f32_e32 v59, v59
	v_mul_f32_e32 v56, 0xbfb8aa3b, v16
	v_mul_f32_e32 v57, 0xbfb8aa3b, v17
	v_add_f32_e32 v58, 1.0, v58
	v_add_f32_e32 v59, 1.0, v59
	v_rcp_f32_e32 v58, v58
	v_rcp_f32_e32 v59, v59
	v_exp_f32_e32 v56, v56
	v_exp_f32_e32 v57, v57
	v_mov_b32_e32 v60, v97
	v_mov_b32_e32 v61, v97
	v_pk_mul_f32 v[18:19], v[18:19], v[58:59]
	v_mov_b32_dpp v60, v12 row_ror:1 row_mask:0xf bank_mask:0xf
	v_mov_b32_dpp v61, v13 row_ror:1 row_mask:0xf bank_mask:0xf
	v_cndmask_b32_e64 v59, v67, 0, s[12:13]
	v_cndmask_b32_e64 v58, v65, 0, s[12:13]
	v_pk_fma_f32 v[32:33], v[32:33], v[58:59], v[36:37]
	v_cndmask_b32_e64 v37, v61, v66, s[10:11]
	v_cndmask_b32_e64 v36, v60, v64, s[10:11]
	v_add_f32_e32 v56, 1.0, v56
	v_add_f32_e32 v57, 1.0, v57
	v_pk_mul_f32 v[28:29], v[28:29], v[36:37]
	v_rcp_f32_e32 v56, v56
	v_rcp_f32_e32 v57, v57
	v_pk_fma_f32 v[24:25], v[12:13], v[24:25], v[28:29]
	v_mov_b32_e32 v62, v97
	v_pk_add_f32 v[24:25], v[32:33], v[24:25]
	v_mov_b32_e32 v63, v97
	v_mul_f32_e32 v28, 0xbfb8aa3b, v24
	v_mul_f32_e32 v29, 0xbfb8aa3b, v25
	v_exp_f32_e32 v28, v28
	v_exp_f32_e32 v29, v29
	v_pk_mul_f32 v[16:17], v[16:17], v[56:57]
	v_mov_b32_dpp v62, v14 row_ror:1 row_mask:0xf bank_mask:0xf
	v_mov_b32_dpp v63, v15 row_ror:1 row_mask:0xf bank_mask:0xf
	v_cndmask_b32_e64 v57, v75, 0, s[12:13]
	v_cndmask_b32_e64 v56, v73, 0, s[12:13]
	v_pk_fma_f32 v[34:35], v[34:35], v[56:57], v[38:39]
	v_cndmask_b32_e64 v39, v63, v74, s[10:11]
	v_cndmask_b32_e64 v38, v62, v72, s[10:11]
	v_pk_mul_f32 v[30:31], v[30:31], v[38:39]
	v_add_f32_e32 v28, 1.0, v28
	v_pk_fma_f32 v[26:27], v[14:15], v[26:27], v[30:31]
	v_add_f32_e32 v29, 1.0, v29
	v_pk_add_f32 v[26:27], v[34:35], v[26:27]
	v_rcp_f32_e32 v28, v28
	v_rcp_f32_e32 v29, v29
	v_mul_f32_e32 v30, 0xbfb8aa3b, v26
	v_mul_f32_e32 v31, 0xbfb8aa3b, v27
	v_exp_f32_e32 v30, v30
	v_exp_f32_e32 v31, v31
	v_pk_mul_f32 v[24:25], v[24:25], v[28:29]
	v_add_co_u32_e32 v28, vcc, s0, v124
	s_mov_b32 s0, 0xc6000
	s_nop 0
	v_addc_co_u32_e32 v29, vcc, 0, v125, vcc
	v_add_f32_e32 v30, 1.0, v30
	v_add_f32_e32 v31, 1.0, v31
	v_cvt_pk_bf16_f32 v56, v46, v47
	v_cvt_pk_bf16_f32 v57, v44, v45
	global_store_dwordx4 v[28:29], v[54:57], off
	v_pk_mul_f32 v[16:17], v[68:69], v[16:17]
	v_rcp_f32_e32 v30, v30
	v_cvt_pk_bf16_f32 v54, v22, v23
	v_cvt_pk_bf16_f32 v55, v20, v21
	v_add_co_u32_e32 v20, vcc, s0, v124
	v_rcp_f32_e32 v31, v31
	s_nop 0
	v_addc_co_u32_e32 v21, vcc, 0, v125, vcc
	s_mov_b32 s0, 0xdc000
	global_store_dwordx4 v[20:21], v[52:55], off
	v_pk_mul_f32 v[18:19], v[70:71], v[18:19]
	v_pk_mul_f32 v[26:27], v[26:27], v[30:31]
	v_cvt_pk_bf16_f32 v52, v16, v17
	v_add_co_u32_e32 v16, vcc, s0, v124
	v_cvt_pk_bf16_f32 v53, v18, v19
	v_pk_mul_f32 v[26:27], v[42:43], v[26:27]
	s_nop 0
	v_addc_co_u32_e32 v17, vcc, 0, v125, vcc
	global_store_dwordx4 v[16:17], v[50:53], off
	v_add_co_u32_e32 v16, vcc, 0xf2000, v124
	v_pk_mul_f32 v[24:25], v[40:41], v[24:25]
	s_nop 0
	v_addc_co_u32_e32 v17, vcc, 0, v125, vcc
	v_cvt_pk_bf16_f32 v50, v24, v25
	v_cvt_pk_bf16_f32 v51, v26, v27
	global_store_dwordx4 v[16:17], v[48:51], off
	s_and_saveexec_b64 s[10:11], s[8:9]
	s_cbranch_execz .LBB0_1054
	v_cndmask_b32_e64 v6, v6, v2, s[6:7]
	v_cndmask_b32_e64 v3, v7, v3, s[6:7]
	v_cndmask_b32_e64 v2, v4, v0, s[6:7]
	v_cndmask_b32_e64 v4, v5, v1, s[6:7]
	v_cndmask_b32_e64 v5, v14, v10, s[6:7]
	v_lshl_add_u64 v[0:1], v[126:127], 1, v[80:81]
	v_cndmask_b32_e64 v7, v15, v11, s[6:7]
	v_cndmask_b32_e64 v8, v12, v8, s[6:7]
	v_cndmask_b32_e64 v9, v13, v9, s[6:7]
	v_cvt_pk_bf16_f32 v2, v2, v4
	v_cvt_pk_bf16_f32 v3, v6, v3
	v_cvt_pk_bf16_f32 v4, v8, v9
	v_cvt_pk_bf16_f32 v5, v5, v7
	global_store_dwordx2 v[0:1], v[2:3], off
	v_add_co_u32_e32 v0, vcc, 0x1000, v0
	s_nop 1
	v_addc_co_u32_e32 v1, vcc, 0, v1, vcc
	global_store_dwordx2 v[0:1], v[4:5], off offset:1536
